# conversion waves of both attention phases: rolling double-buffered weight loads (next item's load i+1 issued as item's load i is consumed), on top of early barrier invalidate
# speedup vs baseline: 1.0204x; 1.0154x over previous
.LBB0_1133:
	s_andn2_b64 vcc, exec, s[6:7]
	s_cbranch_vccnz .LBB0_1209
	s_load_dwordx2 s[22:23], s[0:1], 0xf0
	s_and_b32 s6, s90, 0xffffffc0
	v_mbcnt_hi_u32_b32 v51, -1, v254
	v_mov_b32_e32 v52, v51
	s_waitcnt lgkmcnt(0)
	s_add_u32 s3, s22, 0x421d8000
	s_addc_u32 s52, s23, 0
	s_add_u32 s24, s22, 0x3efd8000
	s_addc_u32 s25, s23, 0
	s_add_u32 s26, s22, 0x441d8000
	s_addc_u32 s27, s23, 0
	s_cmpk_gt_u32 s90, 0xff
	v_add_u32_e32 v50, s6, v52
	v_and_b32_e32 v53, 63, v52
	s_mov_b64 s[6:7], -1
	s_cbranch_scc0 .LBB0_1178
	s_lshl_b32 s6, s92, 2
	s_add_i32 s6, s6, s33
	s_add_i32 s53, s6, 0x27fc
	s_mov_b32 s99, 0
	s_cmpk_gt_i32 s92, 0x2ff
	v_lshlrev_b32_e32 v54, 2, v53
	s_cbranch_scc1 .LBB0_1169
	v_lshlrev_b32_e32 v0, 4, v52
	s_mov_b32 s14, 0x2aaaaaab
	v_and_b32_e32 v20, 0x70, v0
	v_mul_hi_i32 v0, v50, s14
	v_lshrrev_b32_e32 v1, 31, v0
	v_ashrrev_i32_e32 v0, 2, v0
	v_add_u32_e32 v56, v0, v1
	v_add_u32_e32 v1, 0x200, v50
	v_mul_hi_i32 v2, v1, s14
	v_lshrrev_b32_e32 v3, 31, v2
	v_ashrrev_i32_e32 v2, 2, v2
	v_add_u32_e32 v57, v2, v3
	v_add_u32_e32 v3, 0x400, v50
	v_mul_hi_i32 v4, v3, s14
	v_mul_lo_u32 v0, v56, 24
	v_lshrrev_b32_e32 v5, 31, v4
	v_ashrrev_i32_e32 v4, 2, v4
	v_sub_u32_e32 v0, v50, v0
	v_mul_lo_u32 v2, v57, 24
	v_add_u32_e32 v58, v4, v5
	v_mov_b32_e32 v23, 0
	v_lshlrev_b32_e32 v22, 3, v0
	v_sub_u32_e32 v2, v1, v2
	v_mul_lo_u32 v4, v58, 24
	s_movk_i32 s20, 0x190
	s_add_u32 s48, s22, 0x33d8000
	v_lshl_add_u64 v[26:27], v[22:23], 1, s[24:25]
	v_ashrrev_i32_e32 v29, 31, v22
	v_mov_b32_e32 v28, v22
	v_lshlrev_b32_e32 v22, 3, v2
	v_sub_u32_e32 v3, v3, v4
	v_mul_lo_u32 v61, v56, s20
	v_mul_lo_u32 v63, v57, s20
	v_mul_lo_u32 v65, v58, s20
	s_addc_u32 s49, s23, 0
	v_mov_b32_e32 v21, v23
	v_cmp_gt_i32_e64 s[6:7], 16, v0
	v_cmp_lt_i32_e64 s[8:9], 15, v0
	v_cmp_gt_i32_e64 s[10:11], 16, v2
	v_cmp_lt_i32_e64 s[12:13], 15, v2
	v_lshl_add_u64 v[30:31], v[22:23], 1, s[24:25]
	v_ashrrev_i32_e32 v33, 31, v22
	v_mov_b32_e32 v32, v22
	v_lshlrev_b32_e32 v22, 3, v3
	v_ashrrev_i32_e32 v59, 3, v50
	v_ashrrev_i32_e32 v60, 3, v1
	v_add_u32_e32 v1, 0, v61
	v_lshlrev_b32_e32 v62, 4, v0
	v_add_u32_e32 v0, 0, v63
	v_lshlrev_b32_e32 v64, 4, v2
	v_add_u32_e32 v2, 0, v65
	v_lshlrev_b32_e32 v66, 4, v3
	s_movk_i32 s20, 0x88
	s_add_u32 s54, s22, 0x233d8000
	s_movk_i32 s28, 0xff00
	v_lshl_add_u64 v[24:25], s[26:27], 0, v[20:21]
	s_mov_b32 s21, 0
	v_add_u32_e32 v21, 0, v20
	v_and_b32_e32 v55, 0x7c, v54
	v_cmp_gt_i32_e64 s[14:15], 16, v3
	v_cmp_lt_i32_e64 s[16:17], 15, v3
	v_lshl_add_u64 v[34:35], v[22:23], 1, s[24:25]
	v_ashrrev_i32_e32 v37, 31, v22
	v_mov_b32_e32 v36, v22
	v_mul_lo_u32 v67, v59, s20
	v_mul_lo_u32 v68, v60, s20
	s_addc_u32 s55, s23, 0
	s_mov_b32 s29, -1
	v_add_u32_e32 v69, v1, v62
	v_add_u32_e32 v70, v0, v64
	v_add_u32_e32 v71, v2, v66
	s_movk_i32 s63, 0x6400
	s_movk_i32 s64, 0x2000
	s_movk_i32 s65, 0x4000
	s_movk_i32 s66, 0x6000
	s_mov_b32 s67, 0x8000
	s_mov_b32 s68, 0xa000
	s_mov_b32 s69, 0xc000
	s_mov_b32 s70, 0xe000
	s_mov_b32 s71, 0x10000
	s_mov_b32 s72, 0x12000
	s_mov_b32 s73, 0x14000
	s_mov_b32 s74, 0x16000
	s_mov_b32 s75, 0x18000
	s_mov_b32 s76, 0x1a000
	s_mov_b32 s77, 0x1c000
	s_mov_b32 s78, 0x1e000
	s_mov_b32 s79, s92
	s_branch .LBB0_1138

.LBB0_1156:
	s_add_i32 s83, s84, 1
	s_cmp_lt_u32 s83, s35
	s_cselect_b64 s[36:37], -1, 0
	s_cmp_ge_u32 s83, s35
	s_cbranch_scc1 .LBB0_1162
	s_cmp_lt_u32 s83, s81
	s_cselect_b32 s20, 0, s81
	s_cselect_b32 s38, s34, s80
	s_lshl_b32 s20, s20, 6
	s_sub_i32 s20, s38, s20
	s_add_i32 s38, s82, s20
	v_add_u32_e32 v0, s38, v56
	v_add_u32_e32 v4, s38, v57
	v_add_u32_e32 v8, s38, v58
	v_ashrrev_i32_e32 v1, 31, v0
	v_ashrrev_i32_e32 v5, 31, v4
	v_ashrrev_i32_e32 v9, 31, v8
	v_lshlrev_b64 v[2:3], 11, v[0:1]
	v_lshlrev_b64 v[0:1], 7, v[0:1]
	v_lshlrev_b64 v[6:7], 11, v[4:5]
	v_lshlrev_b64 v[4:5], 7, v[4:5]
	v_lshlrev_b64 v[10:11], 11, v[8:9]
	v_lshlrev_b64 v[8:9], 7, v[8:9]
	v_lshl_add_u64 v[0:1], v[26:27], 0, v[0:1]
	v_lshl_add_u64 v[4:5], v[30:31], 0, v[4:5]
	v_lshl_add_u64 v[8:9], v[34:35], 0, v[8:9]
	s_ashr_i32 s39, s38, 31
	v_lshl_add_u64 v[2:3], v[42:43], 0, v[2:3]
	v_lshl_add_u64 v[0:1], v[0:1], 0, s[28:29]
	v_lshl_add_u64 v[6:7], v[44:45], 0, v[6:7]
	v_lshl_add_u64 v[4:5], v[4:5], 0, s[28:29]
	v_lshl_add_u64 v[10:11], v[46:47], 0, v[10:11]
	v_lshl_add_u64 v[8:9], v[8:9], 0, s[28:29]
	v_lshl_add_u64 v[12:13], s[38:39], 1, v[24:25]
	v_cndmask_b32_e64 v1, v1, v3, s[6:7]
	v_cndmask_b32_e64 v0, v0, v2, s[6:7]
	v_cndmask_b32_e64 v5, v5, v7, s[10:11]
	v_cndmask_b32_e64 v4, v4, v6, s[10:11]
	v_cndmask_b32_e64 v9, v9, v11, s[14:15]
	v_cndmask_b32_e64 v8, v8, v10, s[14:15]
	v_lshl_add_u64 v[14:15], v[12:13], 0, v[38:39]
	v_lshl_add_u64 v[16:17], v[12:13], 0, v[40:41]
	global_load_dwordx4 v[0:3], v[0:1], off
	s_nop 0
	global_load_dwordx4 v[4:7], v[4:5], off
	s_nop 0
	global_load_dwordx4 v[8:11], v[8:9], off
	s_nop 0
	global_load_dwordx4 v[12:15], v[14:15], off
	s_nop 0
	global_load_dwordx4 v[16:19], v[16:17], off
	s_cmp_eq_u32 s99, 1
	s_cbranch_scc1 .Lp5_st1
	s_cmp_eq_u32 s99, 2
	s_cbranch_scc1 .Lp5_st2
	s_cmp_gt_i32 s53, 0xbfff
	s_cbranch_scc1 .LBB0_1159
	s_add_i32 s20, s83, 1
	s_cmp_ge_u32 s20, s35
	s_cbranch_scc1 .LBB0_1159
	s_ashr_i32 s20, s53, 10
	s_mul_hi_i32 s38, s20, 0x55555556
	s_lshr_b32 s39, s38, 31
	s_add_i32 s40, s38, s39
	s_mul_i32 s38, s40, 3
	s_sub_i32 s44, s20, s38
	s_lshl_b32 s20, s53, 8
	s_ashr_i32 s45, s44, 31
	s_and_b32 s20, s20, 0x700
	s_lshl_b64 s[38:39], s[44:45], 3
	s_add_u32 s42, s0, s38
	s_addc_u32 s43, s1, s39
	s_ashr_i32 s41, s40, 31
	v_or_b32_e32 v22, s20, v54
	s_cmp_lg_u32 s44, 2
	s_mov_b64 s[46:47], -1
	s_cbranch_scc0 .Lp5_i1_1165
	v_lshlrev_b32_e32 v226, 1, v22
	s_lshl_b64 s[38:39], s[40:41], 23
	v_and_b32_e32 v226, 0xf00, v226
	v_lshl_or_b32 v227, s44, 7, v55
	s_add_u32 s38, s48, s38
	v_add_u32_e32 v226, v227, v226
	s_addc_u32 s39, s49, s39
	s_mov_b64 s[46:47], 0
.Lp5_i1_1165:
	s_load_dwordx2 s[42:43], s[42:43], 0xc0
	s_andn2_b64 vcc, exec, s[46:47]
	s_lshl_b64 s[44:45], s[40:41], 22
	s_cbranch_vccnz .Lp5_i1_1167
	s_add_u32 s38, s54, s44
	s_mov_b64 s[40:41], 0x800
	s_addc_u32 s39, s55, s45
	s_mov_b32 s41, 0x42800000
	v_mov_b32_e32 v226, v22
	s_branch .Lp5_i1_1168

.Lp5_i1_1168:
	s_lshl_b64 s[44:45], s[44:45], 2
	s_waitcnt lgkmcnt(0)
	s_add_u32 s20, s42, s44
	s_addc_u32 s43, s43, s45
	s_bfe_u32 s44, s53, 0x70003
	s_lshl_b32 s42, s44, 17
	s_add_u32 s42, s20, s42
	s_addc_u32 s43, s43, 0
	v_lshlrev_b32_e32 v22, 2, v22
	v_lshl_add_u64 v[230:231], s[42:43], 0, v[22:23]
	global_load_dwordx4 v[72:75], v22, s[42:43] nt
	s_nop 0
	v_mov_b32_e32 v136, v23
	v_mov_b32_e32 v137, v23
	v_mov_b32_e32 v138, v23
	v_mov_b32_e32 v139, v23
	v_mov_b32_e32 v140, v23
	v_mov_b32_e32 v141, v23
	v_mov_b32_e32 v142, v23
	v_mov_b32_e32 v143, v23
	v_mov_b32_e32 v144, v23
	v_mov_b32_e32 v145, v23
	v_mov_b32_e32 v146, v23
	v_mov_b32_e32 v147, v23
	s_mul_i32 s20, s40, s44
	v_ashrrev_i32_e32 v227, 31, v226
	v_lshl_add_u64 v[226:227], s[20:21], 0, v[226:227]
	v_lshl_add_u64 v[226:227], v[226:227], 4, s[38:39]
	s_mov_b32 s98, s41
	s_addk_i32 s53, 0x400
	v_add_co_u32_e32 v76, vcc, s64, v230
	v_addc_co_u32_e32 v77, vcc, 0, v231, vcc
	global_load_dwordx4 v[76:79], v[76:77], off nt
	s_nop 0
	v_add_co_u32_e32 v80, vcc, s65, v230
	v_addc_co_u32_e32 v81, vcc, 0, v231, vcc
	global_load_dwordx4 v[80:83], v[80:81], off nt
	s_nop 0
	v_add_co_u32_e32 v84, vcc, s66, v230
	v_addc_co_u32_e32 v85, vcc, 0, v231, vcc
	global_load_dwordx4 v[84:87], v[84:85], off nt
	s_nop 0
	v_add_co_u32_e32 v88, vcc, s67, v230
	v_addc_co_u32_e32 v89, vcc, 0, v231, vcc
	global_load_dwordx4 v[88:91], v[88:89], off nt
	s_nop 0
	v_add_co_u32_e32 v92, vcc, s68, v230
	v_addc_co_u32_e32 v93, vcc, 0, v231, vcc
	global_load_dwordx4 v[92:95], v[92:93], off nt
	s_nop 0
	v_add_co_u32_e32 v96, vcc, s69, v230
	v_addc_co_u32_e32 v97, vcc, 0, v231, vcc
	global_load_dwordx4 v[96:99], v[96:97], off nt
	s_nop 0
	v_add_co_u32_e32 v100, vcc, s70, v230
	v_addc_co_u32_e32 v101, vcc, 0, v231, vcc
	global_load_dwordx4 v[100:103], v[100:101], off nt
	s_nop 0
	v_add_co_u32_e32 v104, vcc, s71, v230
	v_addc_co_u32_e32 v105, vcc, 0, v231, vcc
	global_load_dwordx4 v[104:107], v[104:105], off nt
	s_nop 0
	v_add_co_u32_e32 v108, vcc, s72, v230
	v_addc_co_u32_e32 v109, vcc, 0, v231, vcc
	global_load_dwordx4 v[108:111], v[108:109], off nt
	s_nop 0
	v_add_co_u32_e32 v112, vcc, s73, v230
	v_addc_co_u32_e32 v113, vcc, 0, v231, vcc
	global_load_dwordx4 v[112:115], v[112:113], off nt
	s_nop 0
	v_add_co_u32_e32 v116, vcc, s74, v230
	v_addc_co_u32_e32 v117, vcc, 0, v231, vcc
	global_load_dwordx4 v[116:119], v[116:117], off nt
	s_nop 0
	v_add_co_u32_e32 v120, vcc, s75, v230
	v_addc_co_u32_e32 v121, vcc, 0, v231, vcc
	global_load_dwordx4 v[120:123], v[120:121], off nt
	s_nop 0
	v_add_co_u32_e32 v124, vcc, s76, v230
	v_addc_co_u32_e32 v125, vcc, 0, v231, vcc
	global_load_dwordx4 v[124:127], v[124:125], off nt
	s_nop 0
	v_add_co_u32_e32 v128, vcc, s77, v230
	v_addc_co_u32_e32 v129, vcc, 0, v231, vcc
	global_load_dwordx4 v[128:131], v[128:129], off nt
	s_nop 0
	v_add_co_u32_e32 v132, vcc, s78, v230
	v_addc_co_u32_e32 v133, vcc, 0, v231, vcc
	global_load_dwordx4 v[132:135], v[132:133], off nt
	s_nop 0
	s_mov_b32 s99, 1
	s_waitcnt vmcnt(16)
	s_andn2_b32 s20, 1, s84
	s_mul_i32 s20, s20, 0xa800
	s_add_i32 s20, s20, 0
	v_add3_u32 v22, s20, v61, v62
	ds_write_b128 v22, v[0:3]
	v_add3_u32 v22, s20, v63, v64
	ds_write_b128 v22, v[4:7]
	v_add3_u32 v22, s20, v65, v66
	ds_write_b128 v22, v[8:11]
	v_add_u32_e32 v22, s20, v20
	v_add3_u32 v48, v22, v67, s63
	v_add3_u32 v22, v22, v68, s63
	ds_write2_b64 v48, v[12:13], v[14:15] offset1:1
	ds_write2_b64 v22, v[16:17], v[18:19] offset1:1
	s_branch .LBB0_1160
.Lp5_st1:
	s_cmp_gt_i32 s53, 0xbfff
	s_cbranch_scc1 .Lp5_st1c
	s_add_i32 s20, s83, 1
	s_cmp_ge_u32 s20, s35
	s_cbranch_scc1 .Lp5_st1c
	v_mov_b32_e32 v225, 0
	s_ashr_i32 s20, s53, 10
	s_mul_hi_i32 s38, s20, 0x55555556
	s_lshr_b32 s39, s38, 31
	s_add_i32 s40, s38, s39
	s_mul_i32 s38, s40, 3
	s_sub_i32 s44, s20, s38
	s_lshl_b32 s20, s53, 8
	s_ashr_i32 s45, s44, 31
	s_and_b32 s20, s20, 0x700
	s_lshl_b64 s[38:39], s[44:45], 3
	s_add_u32 s42, s0, s38
	s_addc_u32 s43, s1, s39
	s_ashr_i32 s41, s40, 31
	v_or_b32_e32 v224, s20, v54
	s_cmp_lg_u32 s44, 2
	s_mov_b64 s[46:47], -1
	s_cbranch_scc0 .Lp5_i2_1165
	v_lshlrev_b32_e32 v228, 1, v224
	s_lshl_b64 s[38:39], s[40:41], 23
	v_and_b32_e32 v228, 0xf00, v228
	v_lshl_or_b32 v229, s44, 7, v55
	s_add_u32 s38, s48, s38
	v_add_u32_e32 v228, v229, v228
	s_addc_u32 s39, s49, s39
	s_mov_b64 s[46:47], 0
.Lp5_i2_1165:
	s_load_dwordx2 s[42:43], s[42:43], 0xc0
	s_andn2_b64 vcc, exec, s[46:47]
	s_lshl_b64 s[44:45], s[40:41], 22
	s_cbranch_vccnz .Lp5_i2_1167
	s_add_u32 s38, s54, s44
	s_mov_b64 s[40:41], 0x800
	s_addc_u32 s39, s55, s45
	s_mov_b32 s41, 0x42800000
	v_mov_b32_e32 v228, v224
	s_branch .Lp5_i2_1168

.Lp5_i2_1168:
	s_lshl_b64 s[44:45], s[44:45], 2
	s_waitcnt lgkmcnt(0)
	s_add_u32 s20, s42, s44
	s_addc_u32 s43, s43, s45
	s_bfe_u32 s44, s53, 0x70003
	s_lshl_b32 s42, s44, 17
	s_add_u32 s42, s20, s42
	s_addc_u32 s43, s43, 0
	v_lshlrev_b32_e32 v224, 2, v224
	v_lshl_add_u64 v[232:233], s[42:43], 0, v[224:225]
	global_load_dwordx4 v[148:151], v224, s[42:43] nt
	s_nop 0
	v_mov_b32_e32 v212, v23
	v_mov_b32_e32 v213, v23
	v_mov_b32_e32 v214, v23
	v_mov_b32_e32 v215, v23
	v_mov_b32_e32 v216, v23
	v_mov_b32_e32 v217, v23
	v_mov_b32_e32 v218, v23
	v_mov_b32_e32 v219, v23
	v_mov_b32_e32 v220, v23
	v_mov_b32_e32 v221, v23
	v_mov_b32_e32 v222, v23
	v_mov_b32_e32 v223, v23
	s_mul_i32 s20, s40, s44
	v_ashrrev_i32_e32 v229, 31, v228
	v_lshl_add_u64 v[228:229], s[20:21], 0, v[228:229]
	v_lshl_add_u64 v[228:229], v[228:229], 4, s[38:39]
	s_mov_b32 s100, s41
	s_addk_i32 s53, 0x400
	s_waitcnt vmcnt(21)
	v_add_co_u32_e32 v152, vcc, s64, v232
	v_addc_co_u32_e32 v153, vcc, 0, v233, vcc
	global_load_dwordx4 v[152:155], v[152:153], off nt
	s_nop 0
	v_mul_f32_e32 v22, s98, v72
	s_waitcnt vmcnt(21)
	v_add_co_u32_e32 v156, vcc, s65, v232
	v_addc_co_u32_e32 v157, vcc, 0, v233, vcc
	global_load_dwordx4 v[156:159], v[156:157], off nt
	s_nop 0
	v_mul_f32_e32 v72, s98, v76
	v_cvt_pk_fp8_f32 v136, v22, v72
	s_waitcnt vmcnt(21)
	v_add_co_u32_e32 v160, vcc, s66, v232
	v_addc_co_u32_e32 v161, vcc, 0, v233, vcc
	global_load_dwordx4 v[160:163], v[160:161], off nt
	s_nop 0
	v_mul_f32_e32 v76, s98, v80
	s_waitcnt vmcnt(21)
	v_add_co_u32_e32 v164, vcc, s67, v232
	v_addc_co_u32_e32 v165, vcc, 0, v233, vcc
	global_load_dwordx4 v[164:167], v[164:165], off nt
	s_nop 0
	v_mul_f32_e32 v80, s98, v84
	s_waitcnt vmcnt(21)
	v_add_co_u32_e32 v168, vcc, s68, v232
	v_addc_co_u32_e32 v169, vcc, 0, v233, vcc
	global_load_dwordx4 v[168:171], v[168:169], off nt
	s_nop 0
	v_mul_f32_e32 v22, s98, v88
	v_cvt_pk_fp8_f32 v136, v76, v80 op_sel:[0,0,1]
	s_waitcnt vmcnt(21)
	v_add_co_u32_e32 v172, vcc, s69, v232
	v_addc_co_u32_e32 v173, vcc, 0, v233, vcc
	global_load_dwordx4 v[172:175], v[172:173], off nt
	s_nop 0
	v_mul_f32_e32 v72, s98, v92
	v_cvt_pk_fp8_f32 v137, v22, v72
	s_waitcnt vmcnt(21)
	v_add_co_u32_e32 v176, vcc, s70, v232
	v_addc_co_u32_e32 v177, vcc, 0, v233, vcc
	global_load_dwordx4 v[176:179], v[176:177], off nt
	s_nop 0
	v_mul_f32_e32 v22, s98, v96
	s_waitcnt vmcnt(21)
	v_add_co_u32_e32 v180, vcc, s71, v232
	v_addc_co_u32_e32 v181, vcc, 0, v233, vcc
	global_load_dwordx4 v[180:183], v[180:181], off nt
	s_nop 0
	v_mul_f32_e32 v72, s98, v100
	v_cvt_pk_fp8_f32 v137, v22, v72 op_sel:[0,0,1]
	s_waitcnt vmcnt(21)
	v_add_co_u32_e32 v184, vcc, s72, v232
	v_addc_co_u32_e32 v185, vcc, 0, v233, vcc
	global_load_dwordx4 v[184:187], v[184:185], off nt
	s_nop 0
	v_mul_f32_e32 v22, s98, v104
	s_waitcnt vmcnt(21)
	v_add_co_u32_e32 v188, vcc, s73, v232
	v_addc_co_u32_e32 v189, vcc, 0, v233, vcc
	global_load_dwordx4 v[188:191], v[188:189], off nt
	s_nop 0
	v_mul_f32_e32 v72, s98, v108
	v_cvt_pk_fp8_f32 v138, v22, v72
	s_waitcnt vmcnt(21)
	v_add_co_u32_e32 v192, vcc, s74, v232
	v_addc_co_u32_e32 v193, vcc, 0, v233, vcc
	global_load_dwordx4 v[192:195], v[192:193], off nt
	s_nop 0
	v_mul_f32_e32 v76, s98, v112
	s_waitcnt vmcnt(21)
	v_add_co_u32_e32 v196, vcc, s75, v232
	v_addc_co_u32_e32 v197, vcc, 0, v233, vcc
	global_load_dwordx4 v[196:199], v[196:197], off nt
	s_nop 0
	v_mul_f32_e32 v80, s98, v116
	s_waitcnt vmcnt(21)
	v_add_co_u32_e32 v200, vcc, s76, v232
	v_addc_co_u32_e32 v201, vcc, 0, v233, vcc
	global_load_dwordx4 v[200:203], v[200:201], off nt
	s_nop 0
	v_mul_f32_e32 v22, s98, v120
	v_cvt_pk_fp8_f32 v138, v76, v80 op_sel:[0,0,1]
	v_mul_f32_e32 v76, s98, v85
	s_waitcnt vmcnt(21)
	v_add_co_u32_e32 v204, vcc, s77, v232
	v_addc_co_u32_e32 v205, vcc, 0, v233, vcc
	global_load_dwordx4 v[204:207], v[204:205], off nt
	s_nop 0
	v_mul_f32_e32 v72, s98, v124
	v_cvt_pk_fp8_f32 v139, v22, v72
	s_waitcnt vmcnt(21)
	v_add_co_u32_e32 v208, vcc, s78, v232
	v_addc_co_u32_e32 v209, vcc, 0, v233, vcc
	global_load_dwordx4 v[208:211], v[208:209], off nt
	s_nop 0
	v_mul_f32_e32 v22, s98, v128
	s_waitcnt vmcnt(21)
	v_mul_f32_e32 v72, s98, v132
	v_cvt_pk_fp8_f32 v139, v22, v72 op_sel:[0,0,1]
	v_mul_f32_e32 v22, s98, v73
	v_mul_f32_e32 v72, s98, v77
	v_cvt_pk_fp8_f32 v140, v22, v72
	v_mul_f32_e32 v22, s98, v89
	v_mul_f32_e32 v72, s98, v93
	v_cvt_pk_fp8_f32 v141, v22, v72
	v_mul_f32_e32 v22, s98, v97
	v_mul_f32_e32 v72, s98, v101
	v_mul_f32_e32 v73, s98, v81
	v_cvt_pk_fp8_f32 v141, v22, v72 op_sel:[0,0,1]
	v_mul_f32_e32 v22, s98, v105
	v_mul_f32_e32 v72, s98, v109
	v_cvt_pk_fp8_f32 v142, v22, v72
	v_mul_f32_e32 v22, s98, v121
	v_mul_f32_e32 v72, s98, v125
	v_cvt_pk_fp8_f32 v143, v22, v72
	v_mul_f32_e32 v22, s98, v129
	v_mul_f32_e32 v72, s98, v133
	v_cvt_pk_fp8_f32 v140, v73, v76 op_sel:[0,0,1]
	v_cvt_pk_fp8_f32 v143, v22, v72 op_sel:[0,0,1]
	v_mul_f32_e32 v22, s98, v74
	v_mul_f32_e32 v72, s98, v78
	v_cvt_pk_fp8_f32 v144, v22, v72
	v_mul_f32_e32 v22, s98, v90
	v_mul_f32_e32 v72, s98, v94
	v_cvt_pk_fp8_f32 v145, v22, v72
	v_mul_f32_e32 v22, s98, v98
	v_mul_f32_e32 v72, s98, v102
	v_mul_f32_e32 v73, s98, v113
	v_cvt_pk_fp8_f32 v145, v22, v72 op_sel:[0,0,1]
	v_mul_f32_e32 v22, s98, v106
	v_mul_f32_e32 v72, s98, v110
	v_cvt_pk_fp8_f32 v146, v22, v72
	v_mul_f32_e32 v22, s98, v122
	v_mul_f32_e32 v72, s98, v126
	v_cvt_pk_fp8_f32 v147, v22, v72
	v_mul_f32_e32 v76, s98, v117
	v_cvt_pk_fp8_f32 v142, v73, v76 op_sel:[0,0,1]
	v_mul_f32_e32 v73, s98, v82
	v_mul_f32_e32 v74, s98, v86
	v_cvt_pk_fp8_f32 v144, v73, v74 op_sel:[0,0,1]
	v_mul_f32_e32 v73, s98, v114
	v_mul_f32_e32 v74, s98, v118
	v_mul_f32_e32 v22, s98, v130
	v_mul_f32_e32 v72, s98, v134
	v_cvt_pk_fp8_f32 v146, v73, v74 op_sel:[0,0,1]
	v_cvt_pk_fp8_f32 v147, v22, v72 op_sel:[0,0,1]
	v_mul_f32_e32 v22, s98, v75
	v_mul_f32_e32 v73, s98, v79
	v_mov_b32_e32 v72, v23
	v_cvt_pk_fp8_f32 v72, v22, v73
	v_mul_f32_e32 v22, s98, v91
	v_mul_f32_e32 v76, s98, v95
	v_mov_b32_e32 v73, v23
	v_cvt_pk_fp8_f32 v73, v22, v76
	v_mul_f32_e32 v74, s98, v83
	v_mul_f32_e32 v75, s98, v87
	v_cvt_pk_fp8_f32 v72, v74, v75 op_sel:[0,0,1]
	v_mul_f32_e32 v22, s98, v99
	v_mul_f32_e32 v74, s98, v103
	v_cvt_pk_fp8_f32 v73, v22, v74 op_sel:[0,0,1]
	v_mul_f32_e32 v22, s98, v107
	v_mul_f32_e32 v75, s98, v111
	v_mov_b32_e32 v74, v23
	v_cvt_pk_fp8_f32 v74, v22, v75
	v_mul_f32_e32 v22, s98, v123
	v_mul_f32_e32 v78, s98, v127
	v_mov_b32_e32 v75, v23
	v_cvt_pk_fp8_f32 v75, v22, v78
	v_mul_f32_e32 v76, s98, v115
	v_mul_f32_e32 v77, s98, v119
	v_cvt_pk_fp8_f32 v74, v76, v77 op_sel:[0,0,1]
	v_mul_f32_e32 v22, s98, v131
	v_mul_f32_e32 v76, s98, v135
	v_cvt_pk_fp8_f32 v75, v22, v76 op_sel:[0,0,1]
	global_store_dwordx4 v[226:227], v[136:139], off
	global_store_dwordx4 v[226:227], v[140:143], off offset:16
	global_store_dwordx4 v[226:227], v[144:147], off offset:32
	global_store_dwordx4 v[226:227], v[72:75], off offset:48
	s_mov_b32 s99, 2
	s_waitcnt vmcnt(20)
	s_andn2_b32 s20, 1, s84
	s_mul_i32 s20, s20, 0xa800
	s_add_i32 s20, s20, 0
	v_add3_u32 v22, s20, v61, v62
	ds_write_b128 v22, v[0:3]
	v_add3_u32 v22, s20, v63, v64
	ds_write_b128 v22, v[4:7]
	v_add3_u32 v22, s20, v65, v66
	ds_write_b128 v22, v[8:11]
	v_add_u32_e32 v22, s20, v20
	v_add3_u32 v48, v22, v67, s63
	v_add3_u32 v22, v22, v68, s63
	ds_write2_b64 v48, v[12:13], v[14:15] offset1:1
	ds_write2_b64 v22, v[16:17], v[18:19] offset1:1
	s_branch .LBB0_1160
.Lp5_st1c:
	s_waitcnt vmcnt(20)
	v_mul_f32_e32 v22, s98, v72
	s_waitcnt vmcnt(19)
	v_mul_f32_e32 v72, s98, v76
	v_cvt_pk_fp8_f32 v136, v22, v72
	s_waitcnt vmcnt(18)
	v_mul_f32_e32 v76, s98, v80
	s_waitcnt vmcnt(17)
	v_mul_f32_e32 v80, s98, v84
	s_waitcnt vmcnt(16)
	v_mul_f32_e32 v22, s98, v88
	v_cvt_pk_fp8_f32 v136, v76, v80 op_sel:[0,0,1]
	s_waitcnt vmcnt(15)
	v_mul_f32_e32 v72, s98, v92
	v_cvt_pk_fp8_f32 v137, v22, v72
	s_waitcnt vmcnt(14)
	v_mul_f32_e32 v22, s98, v96
	s_waitcnt vmcnt(13)
	v_mul_f32_e32 v72, s98, v100
	v_cvt_pk_fp8_f32 v137, v22, v72 op_sel:[0,0,1]
	s_waitcnt vmcnt(12)
	v_mul_f32_e32 v22, s98, v104
	s_waitcnt vmcnt(11)
	v_mul_f32_e32 v72, s98, v108
	v_cvt_pk_fp8_f32 v138, v22, v72
	s_waitcnt vmcnt(10)
	v_mul_f32_e32 v76, s98, v112
	s_waitcnt vmcnt(9)
	v_mul_f32_e32 v80, s98, v116
	s_waitcnt vmcnt(8)
	v_mul_f32_e32 v22, s98, v120
	v_cvt_pk_fp8_f32 v138, v76, v80 op_sel:[0,0,1]
	v_mul_f32_e32 v76, s98, v85
	s_waitcnt vmcnt(7)
	v_mul_f32_e32 v72, s98, v124
	v_cvt_pk_fp8_f32 v139, v22, v72
	s_waitcnt vmcnt(6)
	v_mul_f32_e32 v22, s98, v128
	s_waitcnt vmcnt(5)
	v_mul_f32_e32 v72, s98, v132
	v_cvt_pk_fp8_f32 v139, v22, v72 op_sel:[0,0,1]
	v_mul_f32_e32 v22, s98, v73
	v_mul_f32_e32 v72, s98, v77
	v_cvt_pk_fp8_f32 v140, v22, v72
	v_mul_f32_e32 v22, s98, v89
	v_mul_f32_e32 v72, s98, v93
	v_cvt_pk_fp8_f32 v141, v22, v72
	v_mul_f32_e32 v22, s98, v97
	v_mul_f32_e32 v72, s98, v101
	v_mul_f32_e32 v73, s98, v81
	v_cvt_pk_fp8_f32 v141, v22, v72 op_sel:[0,0,1]
	v_mul_f32_e32 v22, s98, v105
	v_mul_f32_e32 v72, s98, v109
	v_cvt_pk_fp8_f32 v142, v22, v72
	v_mul_f32_e32 v22, s98, v121
	v_mul_f32_e32 v72, s98, v125
	v_cvt_pk_fp8_f32 v143, v22, v72
	v_mul_f32_e32 v22, s98, v129
	v_mul_f32_e32 v72, s98, v133
	v_cvt_pk_fp8_f32 v140, v73, v76 op_sel:[0,0,1]
	v_cvt_pk_fp8_f32 v143, v22, v72 op_sel:[0,0,1]
	v_mul_f32_e32 v22, s98, v74
	v_mul_f32_e32 v72, s98, v78
	v_cvt_pk_fp8_f32 v144, v22, v72
	v_mul_f32_e32 v22, s98, v90
	v_mul_f32_e32 v72, s98, v94
	v_cvt_pk_fp8_f32 v145, v22, v72
	v_mul_f32_e32 v22, s98, v98
	v_mul_f32_e32 v72, s98, v102
	v_mul_f32_e32 v73, s98, v113
	v_cvt_pk_fp8_f32 v145, v22, v72 op_sel:[0,0,1]
	v_mul_f32_e32 v22, s98, v106
	v_mul_f32_e32 v72, s98, v110
	v_cvt_pk_fp8_f32 v146, v22, v72
	v_mul_f32_e32 v22, s98, v122
	v_mul_f32_e32 v72, s98, v126
	v_cvt_pk_fp8_f32 v147, v22, v72
	v_mul_f32_e32 v76, s98, v117
	v_cvt_pk_fp8_f32 v142, v73, v76 op_sel:[0,0,1]
	v_mul_f32_e32 v73, s98, v82
	v_mul_f32_e32 v74, s98, v86
	v_cvt_pk_fp8_f32 v144, v73, v74 op_sel:[0,0,1]
	v_mul_f32_e32 v73, s98, v114
	v_mul_f32_e32 v74, s98, v118
	v_mul_f32_e32 v22, s98, v130
	v_mul_f32_e32 v72, s98, v134
	v_cvt_pk_fp8_f32 v146, v73, v74 op_sel:[0,0,1]
	v_cvt_pk_fp8_f32 v147, v22, v72 op_sel:[0,0,1]
	v_mul_f32_e32 v22, s98, v75
	v_mul_f32_e32 v73, s98, v79
	v_mov_b32_e32 v72, v23
	v_cvt_pk_fp8_f32 v72, v22, v73
	v_mul_f32_e32 v22, s98, v91
	v_mul_f32_e32 v76, s98, v95
	v_mov_b32_e32 v73, v23
	v_cvt_pk_fp8_f32 v73, v22, v76
	v_mul_f32_e32 v74, s98, v83
	v_mul_f32_e32 v75, s98, v87
	v_cvt_pk_fp8_f32 v72, v74, v75 op_sel:[0,0,1]
	v_mul_f32_e32 v22, s98, v99
	v_mul_f32_e32 v74, s98, v103
	v_cvt_pk_fp8_f32 v73, v22, v74 op_sel:[0,0,1]
	v_mul_f32_e32 v22, s98, v107
	v_mul_f32_e32 v75, s98, v111
	v_mov_b32_e32 v74, v23
	v_cvt_pk_fp8_f32 v74, v22, v75
	v_mul_f32_e32 v22, s98, v123
	v_mul_f32_e32 v78, s98, v127
	v_mov_b32_e32 v75, v23
	v_cvt_pk_fp8_f32 v75, v22, v78
	v_mul_f32_e32 v76, s98, v115
	v_mul_f32_e32 v77, s98, v119
	v_cvt_pk_fp8_f32 v74, v76, v77 op_sel:[0,0,1]
	v_mul_f32_e32 v22, s98, v131
	v_mul_f32_e32 v76, s98, v135
	v_cvt_pk_fp8_f32 v75, v22, v76 op_sel:[0,0,1]
	global_store_dwordx4 v[226:227], v[136:139], off
	global_store_dwordx4 v[226:227], v[140:143], off offset:16
	global_store_dwordx4 v[226:227], v[144:147], off offset:32
	global_store_dwordx4 v[226:227], v[72:75], off offset:48
	s_mov_b32 s99, 0
	s_waitcnt vmcnt(4)
	s_andn2_b32 s20, 1, s84
	s_mul_i32 s20, s20, 0xa800
	s_add_i32 s20, s20, 0
	v_add3_u32 v22, s20, v61, v62
	ds_write_b128 v22, v[0:3]
	v_add3_u32 v22, s20, v63, v64
	ds_write_b128 v22, v[4:7]
	v_add3_u32 v22, s20, v65, v66
	ds_write_b128 v22, v[8:11]
	v_add_u32_e32 v22, s20, v20
	v_add3_u32 v48, v22, v67, s63
	v_add3_u32 v22, v22, v68, s63
	ds_write2_b64 v48, v[12:13], v[14:15] offset1:1
	ds_write2_b64 v22, v[16:17], v[18:19] offset1:1
	s_branch .LBB0_1160
.Lp5_st2:
	s_cmp_gt_i32 s53, 0xbfff
	s_cbranch_scc1 .Lp5_st2c
	s_add_i32 s20, s83, 1
	s_cmp_ge_u32 s20, s35
	s_cbranch_scc1 .Lp5_st2c
	s_ashr_i32 s20, s53, 10
	s_mul_hi_i32 s38, s20, 0x55555556
	s_lshr_b32 s39, s38, 31
	s_add_i32 s40, s38, s39
	s_mul_i32 s38, s40, 3
	s_sub_i32 s44, s20, s38
	s_lshl_b32 s20, s53, 8
	s_ashr_i32 s45, s44, 31
	s_and_b32 s20, s20, 0x700
	s_lshl_b64 s[38:39], s[44:45], 3
	s_add_u32 s42, s0, s38
	s_addc_u32 s43, s1, s39
	s_ashr_i32 s41, s40, 31
	v_or_b32_e32 v22, s20, v54
	s_cmp_lg_u32 s44, 2
	s_mov_b64 s[46:47], -1
	s_cbranch_scc0 .Lp5_i3_1165
	v_lshlrev_b32_e32 v226, 1, v22
	s_lshl_b64 s[38:39], s[40:41], 23
	v_and_b32_e32 v226, 0xf00, v226
	v_lshl_or_b32 v227, s44, 7, v55
	s_add_u32 s38, s48, s38
	v_add_u32_e32 v226, v227, v226
	s_addc_u32 s39, s49, s39
	s_mov_b64 s[46:47], 0

.Lp5_i3_1168:
	s_lshl_b64 s[44:45], s[44:45], 2
	s_waitcnt lgkmcnt(0)
	s_add_u32 s20, s42, s44
	s_addc_u32 s43, s43, s45
	s_bfe_u32 s44, s53, 0x70003
	s_lshl_b32 s42, s44, 17
	s_add_u32 s42, s20, s42
	s_addc_u32 s43, s43, 0
	v_lshlrev_b32_e32 v22, 2, v22
	v_lshl_add_u64 v[230:231], s[42:43], 0, v[22:23]
	global_load_dwordx4 v[72:75], v22, s[42:43] nt
	s_nop 0
	v_mov_b32_e32 v136, v23
	v_mov_b32_e32 v137, v23
	v_mov_b32_e32 v138, v23
	v_mov_b32_e32 v139, v23
	v_mov_b32_e32 v140, v23
	v_mov_b32_e32 v141, v23
	v_mov_b32_e32 v142, v23
	v_mov_b32_e32 v143, v23
	v_mov_b32_e32 v144, v23
	v_mov_b32_e32 v145, v23
	v_mov_b32_e32 v146, v23
	v_mov_b32_e32 v147, v23
	s_mul_i32 s20, s40, s44
	v_ashrrev_i32_e32 v227, 31, v226
	v_lshl_add_u64 v[226:227], s[20:21], 0, v[226:227]
	v_lshl_add_u64 v[226:227], v[226:227], 4, s[38:39]
	s_mov_b32 s98, s41
	s_addk_i32 s53, 0x400
	s_waitcnt vmcnt(21)
	v_add_co_u32_e32 v76, vcc, s64, v230
	v_addc_co_u32_e32 v77, vcc, 0, v231, vcc
	global_load_dwordx4 v[76:79], v[76:77], off nt
	s_nop 0
	v_mul_f32_e32 v224, s100, v148
	s_waitcnt vmcnt(21)
	v_add_co_u32_e32 v80, vcc, s65, v230
	v_addc_co_u32_e32 v81, vcc, 0, v231, vcc
	global_load_dwordx4 v[80:83], v[80:81], off nt
	s_nop 0
	v_mul_f32_e32 v148, s100, v152
	v_cvt_pk_fp8_f32 v212, v224, v148
	s_waitcnt vmcnt(21)
	v_add_co_u32_e32 v84, vcc, s66, v230
	v_addc_co_u32_e32 v85, vcc, 0, v231, vcc
	global_load_dwordx4 v[84:87], v[84:85], off nt
	s_nop 0
	v_mul_f32_e32 v152, s100, v156
	s_waitcnt vmcnt(21)
	v_add_co_u32_e32 v88, vcc, s67, v230
	v_addc_co_u32_e32 v89, vcc, 0, v231, vcc
	global_load_dwordx4 v[88:91], v[88:89], off nt
	s_nop 0
	v_mul_f32_e32 v156, s100, v160
	s_waitcnt vmcnt(21)
	v_add_co_u32_e32 v92, vcc, s68, v230
	v_addc_co_u32_e32 v93, vcc, 0, v231, vcc
	global_load_dwordx4 v[92:95], v[92:93], off nt
	s_nop 0
	v_mul_f32_e32 v224, s100, v164
	v_cvt_pk_fp8_f32 v212, v152, v156 op_sel:[0,0,1]
	s_waitcnt vmcnt(21)
	v_add_co_u32_e32 v96, vcc, s69, v230
	v_addc_co_u32_e32 v97, vcc, 0, v231, vcc
	global_load_dwordx4 v[96:99], v[96:97], off nt
	s_nop 0
	v_mul_f32_e32 v148, s100, v168
	v_cvt_pk_fp8_f32 v213, v224, v148
	s_waitcnt vmcnt(21)
	v_add_co_u32_e32 v100, vcc, s70, v230
	v_addc_co_u32_e32 v101, vcc, 0, v231, vcc
	global_load_dwordx4 v[100:103], v[100:101], off nt
	s_nop 0
	v_mul_f32_e32 v224, s100, v172
	s_waitcnt vmcnt(21)
	v_add_co_u32_e32 v104, vcc, s71, v230
	v_addc_co_u32_e32 v105, vcc, 0, v231, vcc
	global_load_dwordx4 v[104:107], v[104:105], off nt
	s_nop 0
	v_mul_f32_e32 v148, s100, v176
	v_cvt_pk_fp8_f32 v213, v224, v148 op_sel:[0,0,1]
	s_waitcnt vmcnt(21)
	v_add_co_u32_e32 v108, vcc, s72, v230
	v_addc_co_u32_e32 v109, vcc, 0, v231, vcc
	global_load_dwordx4 v[108:111], v[108:109], off nt
	s_nop 0
	v_mul_f32_e32 v224, s100, v180
	s_waitcnt vmcnt(21)
	v_add_co_u32_e32 v112, vcc, s73, v230
	v_addc_co_u32_e32 v113, vcc, 0, v231, vcc
	global_load_dwordx4 v[112:115], v[112:113], off nt
	s_nop 0
	v_mul_f32_e32 v148, s100, v184
	v_cvt_pk_fp8_f32 v214, v224, v148
	s_waitcnt vmcnt(21)
	v_add_co_u32_e32 v116, vcc, s74, v230
	v_addc_co_u32_e32 v117, vcc, 0, v231, vcc
	global_load_dwordx4 v[116:119], v[116:117], off nt
	s_nop 0
	v_mul_f32_e32 v152, s100, v188
	s_waitcnt vmcnt(21)
	v_add_co_u32_e32 v120, vcc, s75, v230
	v_addc_co_u32_e32 v121, vcc, 0, v231, vcc
	global_load_dwordx4 v[120:123], v[120:121], off nt
	s_nop 0
	v_mul_f32_e32 v156, s100, v192
	s_waitcnt vmcnt(21)
	v_add_co_u32_e32 v124, vcc, s76, v230
	v_addc_co_u32_e32 v125, vcc, 0, v231, vcc
	global_load_dwordx4 v[124:127], v[124:125], off nt
	s_nop 0
	v_mul_f32_e32 v224, s100, v196
	v_cvt_pk_fp8_f32 v214, v152, v156 op_sel:[0,0,1]
	v_mul_f32_e32 v152, s100, v161
	s_waitcnt vmcnt(21)
	v_add_co_u32_e32 v128, vcc, s77, v230
	v_addc_co_u32_e32 v129, vcc, 0, v231, vcc
	global_load_dwordx4 v[128:131], v[128:129], off nt
	s_nop 0
	v_mul_f32_e32 v148, s100, v200
	v_cvt_pk_fp8_f32 v215, v224, v148
	s_waitcnt vmcnt(21)
	v_add_co_u32_e32 v132, vcc, s78, v230
	v_addc_co_u32_e32 v133, vcc, 0, v231, vcc
	global_load_dwordx4 v[132:135], v[132:133], off nt
	s_nop 0
	v_mul_f32_e32 v224, s100, v204
	s_waitcnt vmcnt(21)
	v_mul_f32_e32 v148, s100, v208
	v_cvt_pk_fp8_f32 v215, v224, v148 op_sel:[0,0,1]
	v_mul_f32_e32 v224, s100, v149
	v_mul_f32_e32 v148, s100, v153
	v_cvt_pk_fp8_f32 v216, v224, v148
	v_mul_f32_e32 v224, s100, v165
	v_mul_f32_e32 v148, s100, v169
	v_cvt_pk_fp8_f32 v217, v224, v148
	v_mul_f32_e32 v224, s100, v173
	v_mul_f32_e32 v148, s100, v177
	v_mul_f32_e32 v149, s100, v157
	v_cvt_pk_fp8_f32 v217, v224, v148 op_sel:[0,0,1]
	v_mul_f32_e32 v224, s100, v181
	v_mul_f32_e32 v148, s100, v185
	v_cvt_pk_fp8_f32 v218, v224, v148
	v_mul_f32_e32 v224, s100, v197
	v_mul_f32_e32 v148, s100, v201
	v_cvt_pk_fp8_f32 v219, v224, v148
	v_mul_f32_e32 v224, s100, v205
	v_mul_f32_e32 v148, s100, v209
	v_cvt_pk_fp8_f32 v216, v149, v152 op_sel:[0,0,1]
	v_cvt_pk_fp8_f32 v219, v224, v148 op_sel:[0,0,1]
	v_mul_f32_e32 v224, s100, v150
	v_mul_f32_e32 v148, s100, v154
	v_cvt_pk_fp8_f32 v220, v224, v148
	v_mul_f32_e32 v224, s100, v166
	v_mul_f32_e32 v148, s100, v170
	v_cvt_pk_fp8_f32 v221, v224, v148
	v_mul_f32_e32 v224, s100, v174
	v_mul_f32_e32 v148, s100, v178
	v_mul_f32_e32 v149, s100, v189
	v_cvt_pk_fp8_f32 v221, v224, v148 op_sel:[0,0,1]
	v_mul_f32_e32 v224, s100, v182
	v_mul_f32_e32 v148, s100, v186
	v_cvt_pk_fp8_f32 v222, v224, v148
	v_mul_f32_e32 v224, s100, v198
	v_mul_f32_e32 v148, s100, v202
	v_cvt_pk_fp8_f32 v223, v224, v148
	v_mul_f32_e32 v152, s100, v193
	v_cvt_pk_fp8_f32 v218, v149, v152 op_sel:[0,0,1]
	v_mul_f32_e32 v149, s100, v158
	v_mul_f32_e32 v150, s100, v162
	v_cvt_pk_fp8_f32 v220, v149, v150 op_sel:[0,0,1]
	v_mul_f32_e32 v149, s100, v190
	v_mul_f32_e32 v150, s100, v194
	v_mul_f32_e32 v224, s100, v206
	v_mul_f32_e32 v148, s100, v210
	v_cvt_pk_fp8_f32 v222, v149, v150 op_sel:[0,0,1]
	v_cvt_pk_fp8_f32 v223, v224, v148 op_sel:[0,0,1]
	v_mul_f32_e32 v224, s100, v151
	v_mul_f32_e32 v149, s100, v155
	v_mov_b32_e32 v148, v23
	v_cvt_pk_fp8_f32 v148, v224, v149
	v_mul_f32_e32 v224, s100, v167
	v_mul_f32_e32 v152, s100, v171
	v_mov_b32_e32 v149, v23
	v_cvt_pk_fp8_f32 v149, v224, v152
	v_mul_f32_e32 v150, s100, v159
	v_mul_f32_e32 v151, s100, v163
	v_cvt_pk_fp8_f32 v148, v150, v151 op_sel:[0,0,1]
	v_mul_f32_e32 v224, s100, v175
	v_mul_f32_e32 v150, s100, v179
	v_cvt_pk_fp8_f32 v149, v224, v150 op_sel:[0,0,1]
	v_mul_f32_e32 v224, s100, v183
	v_mul_f32_e32 v151, s100, v187
	v_mov_b32_e32 v150, v23
	v_cvt_pk_fp8_f32 v150, v224, v151
	v_mul_f32_e32 v224, s100, v199
	v_mul_f32_e32 v154, s100, v203
	v_mov_b32_e32 v151, v23
	v_cvt_pk_fp8_f32 v151, v224, v154
	v_mul_f32_e32 v152, s100, v191
	v_mul_f32_e32 v153, s100, v195
	v_cvt_pk_fp8_f32 v150, v152, v153 op_sel:[0,0,1]
	v_mul_f32_e32 v224, s100, v207
	v_mul_f32_e32 v152, s100, v211
	v_cvt_pk_fp8_f32 v151, v224, v152 op_sel:[0,0,1]
	global_store_dwordx4 v[228:229], v[212:215], off
	global_store_dwordx4 v[228:229], v[216:219], off offset:16
	global_store_dwordx4 v[228:229], v[220:223], off offset:32
	global_store_dwordx4 v[228:229], v[148:151], off offset:48
	s_mov_b32 s99, 1
	s_waitcnt vmcnt(20)
	s_andn2_b32 s20, 1, s84
	s_mul_i32 s20, s20, 0xa800
	s_add_i32 s20, s20, 0
	v_add3_u32 v22, s20, v61, v62
	ds_write_b128 v22, v[0:3]
	v_add3_u32 v22, s20, v63, v64
	ds_write_b128 v22, v[4:7]
	v_add3_u32 v22, s20, v65, v66
	ds_write_b128 v22, v[8:11]
	v_add_u32_e32 v22, s20, v20
	v_add3_u32 v48, v22, v67, s63
	v_add3_u32 v22, v22, v68, s63
	ds_write2_b64 v48, v[12:13], v[14:15] offset1:1
	ds_write2_b64 v22, v[16:17], v[18:19] offset1:1
	s_branch .LBB0_1160
.Lp5_st2c:
	s_waitcnt vmcnt(20)
	v_mul_f32_e32 v224, s100, v148
	s_waitcnt vmcnt(19)
	v_mul_f32_e32 v148, s100, v152
	v_cvt_pk_fp8_f32 v212, v224, v148
	s_waitcnt vmcnt(18)
	v_mul_f32_e32 v152, s100, v156
	s_waitcnt vmcnt(17)
	v_mul_f32_e32 v156, s100, v160
	s_waitcnt vmcnt(16)
	v_mul_f32_e32 v224, s100, v164
	v_cvt_pk_fp8_f32 v212, v152, v156 op_sel:[0,0,1]
	s_waitcnt vmcnt(15)
	v_mul_f32_e32 v148, s100, v168
	v_cvt_pk_fp8_f32 v213, v224, v148
	s_waitcnt vmcnt(14)
	v_mul_f32_e32 v224, s100, v172
	s_waitcnt vmcnt(13)
	v_mul_f32_e32 v148, s100, v176
	v_cvt_pk_fp8_f32 v213, v224, v148 op_sel:[0,0,1]
	s_waitcnt vmcnt(12)
	v_mul_f32_e32 v224, s100, v180
	s_waitcnt vmcnt(11)
	v_mul_f32_e32 v148, s100, v184
	v_cvt_pk_fp8_f32 v214, v224, v148
	s_waitcnt vmcnt(10)
	v_mul_f32_e32 v152, s100, v188
	s_waitcnt vmcnt(9)
	v_mul_f32_e32 v156, s100, v192
	s_waitcnt vmcnt(8)
	v_mul_f32_e32 v224, s100, v196
	v_cvt_pk_fp8_f32 v214, v152, v156 op_sel:[0,0,1]
	v_mul_f32_e32 v152, s100, v161
	s_waitcnt vmcnt(7)
	v_mul_f32_e32 v148, s100, v200
	v_cvt_pk_fp8_f32 v215, v224, v148
	s_waitcnt vmcnt(6)
	v_mul_f32_e32 v224, s100, v204
	s_waitcnt vmcnt(5)
	v_mul_f32_e32 v148, s100, v208
	v_cvt_pk_fp8_f32 v215, v224, v148 op_sel:[0,0,1]
	v_mul_f32_e32 v224, s100, v149
	v_mul_f32_e32 v148, s100, v153
	v_cvt_pk_fp8_f32 v216, v224, v148
	v_mul_f32_e32 v224, s100, v165
	v_mul_f32_e32 v148, s100, v169
	v_cvt_pk_fp8_f32 v217, v224, v148
	v_mul_f32_e32 v224, s100, v173
	v_mul_f32_e32 v148, s100, v177
	v_mul_f32_e32 v149, s100, v157
	v_cvt_pk_fp8_f32 v217, v224, v148 op_sel:[0,0,1]
	v_mul_f32_e32 v224, s100, v181
	v_mul_f32_e32 v148, s100, v185
	v_cvt_pk_fp8_f32 v218, v224, v148
	v_mul_f32_e32 v224, s100, v197
	v_mul_f32_e32 v148, s100, v201
	v_cvt_pk_fp8_f32 v219, v224, v148
	v_mul_f32_e32 v224, s100, v205
	v_mul_f32_e32 v148, s100, v209
	v_cvt_pk_fp8_f32 v216, v149, v152 op_sel:[0,0,1]
	v_cvt_pk_fp8_f32 v219, v224, v148 op_sel:[0,0,1]
	v_mul_f32_e32 v224, s100, v150
	v_mul_f32_e32 v148, s100, v154
	v_cvt_pk_fp8_f32 v220, v224, v148
	v_mul_f32_e32 v224, s100, v166
	v_mul_f32_e32 v148, s100, v170
	v_cvt_pk_fp8_f32 v221, v224, v148
	v_mul_f32_e32 v224, s100, v174
	v_mul_f32_e32 v148, s100, v178
	v_mul_f32_e32 v149, s100, v189
	v_cvt_pk_fp8_f32 v221, v224, v148 op_sel:[0,0,1]
	v_mul_f32_e32 v224, s100, v182
	v_mul_f32_e32 v148, s100, v186
	v_cvt_pk_fp8_f32 v222, v224, v148
	v_mul_f32_e32 v224, s100, v198
	v_mul_f32_e32 v148, s100, v202
	v_cvt_pk_fp8_f32 v223, v224, v148
	v_mul_f32_e32 v152, s100, v193
	v_cvt_pk_fp8_f32 v218, v149, v152 op_sel:[0,0,1]
	v_mul_f32_e32 v149, s100, v158
	v_mul_f32_e32 v150, s100, v162
	v_cvt_pk_fp8_f32 v220, v149, v150 op_sel:[0,0,1]
	v_mul_f32_e32 v149, s100, v190
	v_mul_f32_e32 v150, s100, v194
	v_mul_f32_e32 v224, s100, v206
	v_mul_f32_e32 v148, s100, v210
	v_cvt_pk_fp8_f32 v222, v149, v150 op_sel:[0,0,1]
	v_cvt_pk_fp8_f32 v223, v224, v148 op_sel:[0,0,1]
	v_mul_f32_e32 v224, s100, v151
	v_mul_f32_e32 v149, s100, v155
	v_mov_b32_e32 v148, v23
	v_cvt_pk_fp8_f32 v148, v224, v149
	v_mul_f32_e32 v224, s100, v167
	v_mul_f32_e32 v152, s100, v171
	v_mov_b32_e32 v149, v23
	v_cvt_pk_fp8_f32 v149, v224, v152
	v_mul_f32_e32 v150, s100, v159
	v_mul_f32_e32 v151, s100, v163
	v_cvt_pk_fp8_f32 v148, v150, v151 op_sel:[0,0,1]
	v_mul_f32_e32 v224, s100, v175
	v_mul_f32_e32 v150, s100, v179
	v_cvt_pk_fp8_f32 v149, v224, v150 op_sel:[0,0,1]
	v_mul_f32_e32 v224, s100, v183
	v_mul_f32_e32 v151, s100, v187
	v_mov_b32_e32 v150, v23
	v_cvt_pk_fp8_f32 v150, v224, v151
	v_mul_f32_e32 v224, s100, v199
	v_mul_f32_e32 v154, s100, v203
	v_mov_b32_e32 v151, v23
	v_cvt_pk_fp8_f32 v151, v224, v154
	v_mul_f32_e32 v152, s100, v191
	v_mul_f32_e32 v153, s100, v195
	v_cvt_pk_fp8_f32 v150, v152, v153 op_sel:[0,0,1]
	v_mul_f32_e32 v224, s100, v207
	v_mul_f32_e32 v152, s100, v211
	v_cvt_pk_fp8_f32 v151, v224, v152 op_sel:[0,0,1]
	global_store_dwordx4 v[228:229], v[212:215], off
	global_store_dwordx4 v[228:229], v[216:219], off offset:16
	global_store_dwordx4 v[228:229], v[220:223], off offset:32
	global_store_dwordx4 v[228:229], v[148:151], off offset:48
	s_mov_b32 s99, 0
	s_waitcnt vmcnt(4)
	s_andn2_b32 s20, 1, s84
	s_mul_i32 s20, s20, 0xa800
	s_add_i32 s20, s20, 0
	v_add3_u32 v22, s20, v61, v62
	ds_write_b128 v22, v[0:3]
	v_add3_u32 v22, s20, v63, v64
	ds_write_b128 v22, v[4:7]
	v_add3_u32 v22, s20, v65, v66
	ds_write_b128 v22, v[8:11]
	v_add_u32_e32 v22, s20, v20
	v_add3_u32 v48, v22, v67, s63
	v_add3_u32 v22, v22, v68, s63
	ds_write2_b64 v48, v[12:13], v[14:15] offset1:1
	ds_write2_b64 v22, v[16:17], v[18:19] offset1:1
	s_branch .LBB0_1160

.LBB0_1160:
	s_add_i32 s82, s82, 64
	s_cmp_eq_u32 s35, s83
	s_waitcnt lgkmcnt(0)
	s_barrier
	s_cbranch_scc1 .LBB0_1137
	s_mov_b32 s84, s83
	s_branch .LBB0_1156
.LBB0_1162:
	s_branch .LBB0_1160
.LBB0_1169:
	s_cmp_gt_i32 s53, 0xbfff
	s_cbranch_scc1 .LBB0_1177
	s_load_dwordx2 s[8:9], s[0:1], 0xf0
	s_waitcnt vmcnt(0)
	v_and_b32_e32 v4, 0x7c, v54
	s_mov_b32 s7, 0
	v_mov_b32_e32 v1, 0
	s_movk_i32 s31, 0x2000
	s_waitcnt lgkmcnt(0)
	s_add_u32 s20, s8, 0x33d8000
	s_addc_u32 s21, s9, 0
	s_add_u32 s28, s8, 0x233d8000
	s_addc_u32 s29, s9, 0
	s_lshl_b32 s30, s53, 8
	s_movk_i32 s34, 0x4000
	s_movk_i32 s35, 0x6000
	s_mov_b32 s36, 0x8000
	s_mov_b32 s37, 0xa000
	s_mov_b32 s38, 0xc000
	s_mov_b32 s39, 0xe000
	s_mov_b32 s40, 0x10000
	s_mov_b32 s41, 0x12000
	s_mov_b32 s42, 0x14000
	s_mov_b32 s43, 0x16000
	s_mov_b32 s44, 0x18000
	s_mov_b32 s45, 0x1a000
	s_mov_b32 s46, 0x1c000
	s_mov_b32 s47, 0x1e000
	s_branch .LBB0_1173

.LBB0_2361:
	s_andn2_b64 vcc, exec, s[8:9]
	s_cbranch_vccnz .LBB0_2423
	s_load_dwordx2 s[14:15], s[0:1], 0xf0
	s_and_b32 s3, s90, 0xffffffc0
	s_waitcnt vmcnt(0)
	v_mbcnt_hi_u32_b32 v24, -1, v254
	v_mov_b32_e32 v25, v24
	s_waitcnt lgkmcnt(0)
	s_add_u32 s8, s14, 0x469d8000
	s_addc_u32 s9, s15, 0
	s_add_u32 s10, s14, 0x461d8000
	s_addc_u32 s11, s15, 0
	s_cmpk_gt_u32 s90, 0xff
	v_add_u32_e32 v26, s3, v25
	v_and_b32_e32 v27, 63, v25
	s_mov_b64 s[12:13], -1
	s_cbranch_scc0 .LBB0_2395
	s_lshl_b32 s3, s92, 2
	s_add_i32 s3, s3, s33
	s_add_i32 s3, s3, 0xd7fc
	s_mov_b32 s99, 0
	s_cmpk_gt_i32 s92, 0x5ff
	v_lshlrev_b32_e32 v28, 2, v27
	s_cbranch_scc1 .LBB0_2386
	v_ashrrev_i32_e32 v0, 31, v26
	v_lshrrev_b32_e32 v0, 29, v0
	v_add_u32_e32 v0, v26, v0
	v_ashrrev_i32_e32 v29, 3, v0
	v_and_b32_e32 v0, -8, v0
	s_movk_i32 s12, 0x90
	v_sub_u32_e32 v1, v26, v0
	v_ashrrev_i32_e32 v30, 3, v26
	v_lshlrev_b32_e32 v0, 3, v25
	v_mul_lo_u32 v31, v29, s12
	s_movk_i32 s12, 0x88
	s_add_u32 s28, s14, 0x33d8000
	v_lshlrev_b32_e32 v8, 3, v1
	v_and_b32_e32 v0, 56, v0
	v_mul_lo_u32 v33, v30, s12
	v_lshlrev_b32_e32 v3, 4, v25
	s_addc_u32 s29, s15, 0
	v_ashrrev_i32_e32 v9, 31, v8
	v_mov_b32_e32 v11, 0
	v_add_u32_e32 v2, 0, v31
	v_lshlrev_b32_e32 v32, 4, v1
	v_add_u32_e32 v1, 0, v33
	v_and_b32_e32 v34, 0x70, v3
	v_lshlrev_b32_e32 v10, 1, v0
	s_add_u32 s30, s14, 0x233d8000
	s_movk_i32 s34, 0x2400
	s_mov_b32 s13, 0
	v_lshl_add_u64 v[12:13], v[8:9], 1, s[8:9]
	v_lshl_add_u64 v[14:15], s[10:11], 0, v[10:11]
	v_and_b32_e32 v35, 0x7c, v28
	s_addc_u32 s31, s15, 0
	v_lshlrev_b32_e32 v16, 1, v0
	v_mov_b32_e32 v17, v11
	v_add_u32_e32 v36, v2, v32
	v_add3_u32 v37, v1, v34, s34
	s_movk_i32 s35, 0x2000
	s_movk_i32 s36, 0x4000
	s_movk_i32 s37, 0x6000
	s_mov_b32 s38, 0x8000
	s_mov_b32 s39, 0xa000
	s_mov_b32 s40, 0xc000
	s_mov_b32 s41, 0xe000
	s_mov_b32 s42, 0x10000
	s_mov_b32 s43, 0x12000
	s_mov_b32 s44, 0x14000
	s_mov_b32 s45, 0x16000
	s_mov_b32 s46, 0x18000
	s_mov_b32 s47, 0x1a000
	s_mov_b32 s48, 0x1c000
	s_mov_b32 s49, 0x1e000
	v_mov_b32_e32 v38, 0x80
	s_mov_b32 s50, s92
	s_ashr_i32 s18, s50, 1
	s_cmpk_gt_i32 s18, 0x1ff
	s_mov_b64 s[16:17], -1
	s_cbranch_scc0 .LBB0_2367
	s_branch .LBB0_2366

.LBB0_2372:
	s_add_i32 s63, s64, 1
	s_cmp_lt_i32 s63, s54
	s_cselect_b64 s[16:17], -1, 0
	s_cmp_ge_i32 s63, s54
	s_cbranch_scc1 .LBB0_2378
	s_cmp_lt_i32 s63, s52
	s_cselect_b32 s12, 0, s52
	s_cselect_b32 s18, s51, s53
	s_lshl_b32 s12, s12, 6
	s_sub_i32 s12, s18, s12
	s_add_i32 s18, s55, s12
	v_add_u32_e32 v0, s18, v29
	v_ashrrev_i32_e32 v1, 31, v0
	v_lshlrev_b64 v[0:1], 9, v[0:1]
	s_ashr_i32 s19, s18, 31
	v_lshl_add_u64 v[0:1], v[18:19], 0, v[0:1]
	v_lshl_add_u64 v[4:5], s[18:19], 1, v[20:21]
	global_load_dwordx4 v[0:3], v[0:1], off
	s_nop 0
	global_load_dwordx4 v[4:7], v[4:5], off
	s_cmp_eq_u32 s99, 1
	s_cbranch_scc1 .Lp13_st1
	s_cmp_eq_u32 s99, 2
	s_cbranch_scc1 .Lp13_st2
	s_cmp_gt_i32 s3, 0x16fff
	s_cbranch_scc1 .LBB0_2375
	s_add_i32 s12, s63, 1
	s_cmp_ge_u32 s12, s54
	s_cbranch_scc1 .LBB0_2375
	s_ashr_i32 s12, s3, 10
	s_mul_hi_i32 s18, s12, 0x55555556
	s_lshr_b32 s19, s18, 31
	s_add_i32 s20, s18, s19
	s_mul_i32 s18, s20, 3
	s_sub_i32 s24, s12, s18
	s_lshl_b32 s12, s3, 8
	s_ashr_i32 s25, s24, 31
	s_and_b32 s12, s12, 0x700
	s_lshl_b64 s[18:19], s[24:25], 3
	s_add_u32 s22, s0, s18
	s_addc_u32 s23, s1, s19
	s_ashr_i32 s21, s20, 31
	v_or_b32_e32 v10, s12, v28
	s_cmp_lg_u32 s24, 2
	s_mov_b64 s[26:27], -1
	s_cbranch_scc0 .Lp13_i1_2381
	v_lshlrev_b32_e32 v226, 1, v10
	s_lshl_b64 s[18:19], s[20:21], 23
	v_and_b32_e32 v226, 0xf00, v226
	v_lshl_or_b32 v227, s24, 7, v35
	s_add_u32 s18, s28, s18
	v_add_u32_e32 v226, v227, v226
	s_addc_u32 s19, s29, s19
	s_mov_b64 s[26:27], 0
.Lp13_i1_2381:
	s_load_dwordx2 s[22:23], s[22:23], 0xc0
	s_andn2_b64 vcc, exec, s[26:27]
	s_lshl_b64 s[24:25], s[20:21], 22
	s_cbranch_vccnz .Lp13_i1_2383
	s_add_u32 s18, s30, s24
	s_mov_b64 s[20:21], 0x800
	s_addc_u32 s19, s31, s25
	s_mov_b32 s21, 0x42800000
	v_mov_b32_e32 v226, v10
	s_branch .Lp13_i1_2384

.Lp13_i1_2384:
	s_lshl_b64 s[24:25], s[24:25], 2
	s_waitcnt lgkmcnt(0)
	s_add_u32 s12, s22, s24
	s_addc_u32 s23, s23, s25
	s_bfe_u32 s24, s3, 0x70003
	s_lshl_b32 s22, s24, 17
	s_add_u32 s22, s12, s22
	s_addc_u32 s23, s23, 0
	v_lshlrev_b32_e32 v10, 2, v10
	v_lshl_add_u64 v[230:231], s[22:23], 0, v[10:11]
	global_load_dwordx4 v[40:43], v10, s[22:23] nt
	s_nop 0
	v_mov_b32_e32 v104, v11
	v_mov_b32_e32 v105, v11
	v_mov_b32_e32 v106, v11
	v_mov_b32_e32 v107, v11
	v_mov_b32_e32 v108, v11
	v_mov_b32_e32 v109, v11
	v_mov_b32_e32 v110, v11
	v_mov_b32_e32 v111, v11
	v_mov_b32_e32 v112, v11
	v_mov_b32_e32 v113, v11
	v_mov_b32_e32 v114, v11
	v_mov_b32_e32 v115, v11
	s_mul_i32 s12, s20, s24
	v_ashrrev_i32_e32 v227, 31, v226
	v_lshl_add_u64 v[226:227], s[12:13], 0, v[226:227]
	v_lshl_add_u64 v[226:227], v[226:227], 4, s[18:19]
	s_mov_b32 s98, s21
	s_addk_i32 s3, 0x400
	v_add_co_u32_e32 v44, vcc, s35, v230
	v_addc_co_u32_e32 v45, vcc, 0, v231, vcc
	global_load_dwordx4 v[44:47], v[44:45], off nt
	s_nop 0
	v_add_co_u32_e32 v48, vcc, s36, v230
	v_addc_co_u32_e32 v49, vcc, 0, v231, vcc
	global_load_dwordx4 v[48:51], v[48:49], off nt
	s_nop 0
	v_add_co_u32_e32 v52, vcc, s37, v230
	v_addc_co_u32_e32 v53, vcc, 0, v231, vcc
	global_load_dwordx4 v[52:55], v[52:53], off nt
	s_nop 0
	v_add_co_u32_e32 v56, vcc, s38, v230
	v_addc_co_u32_e32 v57, vcc, 0, v231, vcc
	global_load_dwordx4 v[56:59], v[56:57], off nt
	s_nop 0
	v_add_co_u32_e32 v60, vcc, s39, v230
	v_addc_co_u32_e32 v61, vcc, 0, v231, vcc
	global_load_dwordx4 v[60:63], v[60:61], off nt
	s_nop 0
	v_add_co_u32_e32 v64, vcc, s40, v230
	v_addc_co_u32_e32 v65, vcc, 0, v231, vcc
	global_load_dwordx4 v[64:67], v[64:65], off nt
	s_nop 0
	v_add_co_u32_e32 v68, vcc, s41, v230
	v_addc_co_u32_e32 v69, vcc, 0, v231, vcc
	global_load_dwordx4 v[68:71], v[68:69], off nt
	s_nop 0
	v_add_co_u32_e32 v72, vcc, s42, v230
	v_addc_co_u32_e32 v73, vcc, 0, v231, vcc
	global_load_dwordx4 v[72:75], v[72:73], off nt
	s_nop 0
	v_add_co_u32_e32 v76, vcc, s43, v230
	v_addc_co_u32_e32 v77, vcc, 0, v231, vcc
	global_load_dwordx4 v[76:79], v[76:77], off nt
	s_nop 0
	v_add_co_u32_e32 v80, vcc, s44, v230
	v_addc_co_u32_e32 v81, vcc, 0, v231, vcc
	global_load_dwordx4 v[80:83], v[80:81], off nt
	s_nop 0
	v_add_co_u32_e32 v84, vcc, s45, v230
	v_addc_co_u32_e32 v85, vcc, 0, v231, vcc
	global_load_dwordx4 v[84:87], v[84:85], off nt
	s_nop 0
	v_add_co_u32_e32 v88, vcc, s46, v230
	v_addc_co_u32_e32 v89, vcc, 0, v231, vcc
	global_load_dwordx4 v[88:91], v[88:89], off nt
	s_nop 0
	v_add_co_u32_e32 v92, vcc, s47, v230
	v_addc_co_u32_e32 v93, vcc, 0, v231, vcc
	global_load_dwordx4 v[92:95], v[92:93], off nt
	s_nop 0
	v_add_co_u32_e32 v96, vcc, s48, v230
	v_addc_co_u32_e32 v97, vcc, 0, v231, vcc
	global_load_dwordx4 v[96:99], v[96:97], off nt
	s_nop 0
	v_add_co_u32_e32 v100, vcc, s49, v230
	v_addc_co_u32_e32 v101, vcc, 0, v231, vcc
	global_load_dwordx4 v[100:103], v[100:101], off nt
	s_nop 0
	s_mov_b32 s99, 1
	s_waitcnt vmcnt(16)
	s_andn2_b32 s12, 1, s64
	s_mulk_i32 s12, 0x4600
	s_add_i32 s12, s12, 0
	v_add_u32_e32 v10, s12, v33
	v_add3_u32 v22, s12, v31, v32
	v_add3_u32 v10, v10, v34, s34
	ds_write_b128 v22, v[0:3]
	ds_write2_b64 v10, v[4:5], v[6:7] offset1:1
	s_branch .LBB0_2376
.Lp13_st1:
	s_cmp_gt_i32 s3, 0x16fff
	s_cbranch_scc1 .Lp13_st1c
	s_add_i32 s12, s63, 1
	s_cmp_ge_u32 s12, s54
	s_cbranch_scc1 .Lp13_st1c
	v_mov_b32_e32 v193, 0
	s_ashr_i32 s12, s3, 10
	s_mul_hi_i32 s18, s12, 0x55555556
	s_lshr_b32 s19, s18, 31
	s_add_i32 s20, s18, s19
	s_mul_i32 s18, s20, 3
	s_sub_i32 s24, s12, s18
	s_lshl_b32 s12, s3, 8
	s_ashr_i32 s25, s24, 31
	s_and_b32 s12, s12, 0x700
	s_lshl_b64 s[18:19], s[24:25], 3
	s_add_u32 s22, s0, s18
	s_addc_u32 s23, s1, s19
	s_ashr_i32 s21, s20, 31
	v_or_b32_e32 v192, s12, v28
	s_cmp_lg_u32 s24, 2
	s_mov_b64 s[26:27], -1
	s_cbranch_scc0 .Lp13_i2_2381
	v_lshlrev_b32_e32 v228, 1, v192
	s_lshl_b64 s[18:19], s[20:21], 23
	v_and_b32_e32 v228, 0xf00, v228
	v_lshl_or_b32 v229, s24, 7, v35
	s_add_u32 s18, s28, s18
	v_add_u32_e32 v228, v229, v228
	s_addc_u32 s19, s29, s19
	s_mov_b64 s[26:27], 0
.Lp13_i2_2381:
	s_load_dwordx2 s[22:23], s[22:23], 0xc0
	s_andn2_b64 vcc, exec, s[26:27]
	s_lshl_b64 s[24:25], s[20:21], 22
	s_cbranch_vccnz .Lp13_i2_2383
	s_add_u32 s18, s30, s24
	s_mov_b64 s[20:21], 0x800
	s_addc_u32 s19, s31, s25
	s_mov_b32 s21, 0x42800000
	v_mov_b32_e32 v228, v192
	s_branch .Lp13_i2_2384

.Lp13_i2_2384:
	s_lshl_b64 s[24:25], s[24:25], 2
	s_waitcnt lgkmcnt(0)
	s_add_u32 s12, s22, s24
	s_addc_u32 s23, s23, s25
	s_bfe_u32 s24, s3, 0x70003
	s_lshl_b32 s22, s24, 17
	s_add_u32 s22, s12, s22
	s_addc_u32 s23, s23, 0
	v_lshlrev_b32_e32 v192, 2, v192
	v_lshl_add_u64 v[232:233], s[22:23], 0, v[192:193]
	global_load_dwordx4 v[116:119], v192, s[22:23] nt
	s_nop 0
	v_mov_b32_e32 v180, v11
	v_mov_b32_e32 v181, v11
	v_mov_b32_e32 v182, v11
	v_mov_b32_e32 v183, v11
	v_mov_b32_e32 v184, v11
	v_mov_b32_e32 v185, v11
	v_mov_b32_e32 v186, v11
	v_mov_b32_e32 v187, v11
	v_mov_b32_e32 v188, v11
	v_mov_b32_e32 v189, v11
	v_mov_b32_e32 v190, v11
	v_mov_b32_e32 v191, v11
	s_mul_i32 s12, s20, s24
	v_ashrrev_i32_e32 v229, 31, v228
	v_lshl_add_u64 v[228:229], s[12:13], 0, v[228:229]
	v_lshl_add_u64 v[228:229], v[228:229], 4, s[18:19]
	s_mov_b32 s100, s21
	s_addk_i32 s3, 0x400
	s_waitcnt vmcnt(18)
	v_add_co_u32_e32 v120, vcc, s35, v232
	v_addc_co_u32_e32 v121, vcc, 0, v233, vcc
	global_load_dwordx4 v[120:123], v[120:121], off nt
	s_nop 0
	v_mul_f32_e32 v10, s98, v40
	s_waitcnt vmcnt(18)
	v_add_co_u32_e32 v124, vcc, s36, v232
	v_addc_co_u32_e32 v125, vcc, 0, v233, vcc
	global_load_dwordx4 v[124:127], v[124:125], off nt
	s_nop 0
	v_mul_f32_e32 v39, s98, v44
	v_cvt_pk_fp8_f32 v104, v10, v39
	s_waitcnt vmcnt(18)
	v_add_co_u32_e32 v128, vcc, s37, v232
	v_addc_co_u32_e32 v129, vcc, 0, v233, vcc
	global_load_dwordx4 v[128:131], v[128:129], off nt
	s_nop 0
	v_mul_f32_e32 v40, s98, v48
	s_waitcnt vmcnt(18)
	v_add_co_u32_e32 v132, vcc, s38, v232
	v_addc_co_u32_e32 v133, vcc, 0, v233, vcc
	global_load_dwordx4 v[132:135], v[132:133], off nt
	s_nop 0
	v_mul_f32_e32 v44, s98, v52
	s_waitcnt vmcnt(18)
	v_add_co_u32_e32 v136, vcc, s39, v232
	v_addc_co_u32_e32 v137, vcc, 0, v233, vcc
	global_load_dwordx4 v[136:139], v[136:137], off nt
	s_nop 0
	v_mul_f32_e32 v10, s98, v56
	v_cvt_pk_fp8_f32 v104, v40, v44 op_sel:[0,0,1]
	s_waitcnt vmcnt(18)
	v_add_co_u32_e32 v140, vcc, s40, v232
	v_addc_co_u32_e32 v141, vcc, 0, v233, vcc
	global_load_dwordx4 v[140:143], v[140:141], off nt
	s_nop 0
	v_mul_f32_e32 v39, s98, v60
	v_cvt_pk_fp8_f32 v105, v10, v39
	s_waitcnt vmcnt(18)
	v_add_co_u32_e32 v144, vcc, s41, v232
	v_addc_co_u32_e32 v145, vcc, 0, v233, vcc
	global_load_dwordx4 v[144:147], v[144:145], off nt
	s_nop 0
	v_mul_f32_e32 v10, s98, v64
	s_waitcnt vmcnt(18)
	v_add_co_u32_e32 v148, vcc, s42, v232
	v_addc_co_u32_e32 v149, vcc, 0, v233, vcc
	global_load_dwordx4 v[148:151], v[148:149], off nt
	s_nop 0
	v_mul_f32_e32 v39, s98, v68
	v_cvt_pk_fp8_f32 v105, v10, v39 op_sel:[0,0,1]
	s_waitcnt vmcnt(18)
	v_add_co_u32_e32 v152, vcc, s43, v232
	v_addc_co_u32_e32 v153, vcc, 0, v233, vcc
	global_load_dwordx4 v[152:155], v[152:153], off nt
	s_nop 0
	v_mul_f32_e32 v10, s98, v72
	s_waitcnt vmcnt(18)
	v_add_co_u32_e32 v156, vcc, s44, v232
	v_addc_co_u32_e32 v157, vcc, 0, v233, vcc
	global_load_dwordx4 v[156:159], v[156:157], off nt
	s_nop 0
	v_mul_f32_e32 v39, s98, v76
	v_cvt_pk_fp8_f32 v106, v10, v39
	s_waitcnt vmcnt(18)
	v_add_co_u32_e32 v160, vcc, s45, v232
	v_addc_co_u32_e32 v161, vcc, 0, v233, vcc
	global_load_dwordx4 v[160:163], v[160:161], off nt
	s_nop 0
	v_mul_f32_e32 v40, s98, v80
	s_waitcnt vmcnt(18)
	v_add_co_u32_e32 v164, vcc, s46, v232
	v_addc_co_u32_e32 v165, vcc, 0, v233, vcc
	global_load_dwordx4 v[164:167], v[164:165], off nt
	s_nop 0
	v_mul_f32_e32 v44, s98, v84
	s_waitcnt vmcnt(18)
	v_add_co_u32_e32 v168, vcc, s47, v232
	v_addc_co_u32_e32 v169, vcc, 0, v233, vcc
	global_load_dwordx4 v[168:171], v[168:169], off nt
	s_nop 0
	v_mul_f32_e32 v10, s98, v88
	v_cvt_pk_fp8_f32 v106, v40, v44 op_sel:[0,0,1]
	v_mul_f32_e32 v40, s98, v49
	v_mul_f32_e32 v44, s98, v83
	s_waitcnt vmcnt(18)
	v_add_co_u32_e32 v172, vcc, s48, v232
	v_addc_co_u32_e32 v173, vcc, 0, v233, vcc
	global_load_dwordx4 v[172:175], v[172:173], off nt
	s_nop 0
	v_mul_f32_e32 v39, s98, v92
	v_cvt_pk_fp8_f32 v107, v10, v39
	s_waitcnt vmcnt(18)
	v_add_co_u32_e32 v176, vcc, s49, v232
	v_addc_co_u32_e32 v177, vcc, 0, v233, vcc
	global_load_dwordx4 v[176:179], v[176:177], off nt
	s_nop 0
	v_mul_f32_e32 v10, s98, v96
	s_waitcnt vmcnt(18)
	v_mul_f32_e32 v39, s98, v100
	v_cvt_pk_fp8_f32 v107, v10, v39 op_sel:[0,0,1]
	v_mul_f32_e32 v10, s98, v41
	v_mul_f32_e32 v39, s98, v45
	v_cvt_pk_fp8_f32 v108, v10, v39
	v_mul_f32_e32 v10, s98, v57
	v_mul_f32_e32 v39, s98, v61
	v_cvt_pk_fp8_f32 v109, v10, v39
	v_mul_f32_e32 v10, s98, v65
	v_mul_f32_e32 v39, s98, v69
	v_mul_f32_e32 v41, s98, v53
	v_cvt_pk_fp8_f32 v109, v10, v39 op_sel:[0,0,1]
	v_mul_f32_e32 v10, s98, v73
	v_mul_f32_e32 v39, s98, v77
	v_cvt_pk_fp8_f32 v110, v10, v39
	v_mul_f32_e32 v10, s98, v89
	v_mul_f32_e32 v39, s98, v93
	v_cvt_pk_fp8_f32 v111, v10, v39
	v_mul_f32_e32 v10, s98, v97
	v_mul_f32_e32 v39, s98, v101
	v_cvt_pk_fp8_f32 v108, v40, v41 op_sel:[0,0,1]
	v_cvt_pk_fp8_f32 v111, v10, v39 op_sel:[0,0,1]
	v_mul_f32_e32 v10, s98, v42
	v_mul_f32_e32 v39, s98, v46
	v_cvt_pk_fp8_f32 v112, v10, v39
	v_mul_f32_e32 v10, s98, v58
	v_mul_f32_e32 v39, s98, v62
	v_cvt_pk_fp8_f32 v113, v10, v39
	v_mul_f32_e32 v10, s98, v66
	v_mul_f32_e32 v39, s98, v70
	v_mul_f32_e32 v40, s98, v81
	v_cvt_pk_fp8_f32 v113, v10, v39 op_sel:[0,0,1]
	v_mul_f32_e32 v10, s98, v74
	v_mul_f32_e32 v39, s98, v78
	v_cvt_pk_fp8_f32 v114, v10, v39
	v_mul_f32_e32 v10, s98, v90
	v_mul_f32_e32 v39, s98, v94
	v_cvt_pk_fp8_f32 v115, v10, v39
	v_mul_f32_e32 v41, s98, v85
	v_cvt_pk_fp8_f32 v110, v40, v41 op_sel:[0,0,1]
	v_mul_f32_e32 v40, s98, v50
	v_mul_f32_e32 v41, s98, v54
	v_cvt_pk_fp8_f32 v112, v40, v41 op_sel:[0,0,1]
	v_mul_f32_e32 v40, s98, v82
	v_mul_f32_e32 v41, s98, v86
	v_mul_f32_e32 v10, s98, v98
	v_mul_f32_e32 v39, s98, v102
	v_cvt_pk_fp8_f32 v114, v40, v41 op_sel:[0,0,1]
	v_cvt_pk_fp8_f32 v115, v10, v39 op_sel:[0,0,1]
	v_mul_f32_e32 v10, s98, v43
	v_mul_f32_e32 v39, s98, v47
	v_mov_b32_e32 v40, v11
	v_cvt_pk_fp8_f32 v40, v10, v39
	v_mul_f32_e32 v10, s98, v59
	v_mul_f32_e32 v39, s98, v63
	v_mov_b32_e32 v41, v11
	v_cvt_pk_fp8_f32 v41, v10, v39
	v_mul_f32_e32 v42, s98, v51
	v_mul_f32_e32 v43, s98, v55
	v_mul_f32_e32 v10, s98, v67
	v_mul_f32_e32 v39, s98, v71
	v_cvt_pk_fp8_f32 v40, v42, v43 op_sel:[0,0,1]
	v_cvt_pk_fp8_f32 v41, v10, v39 op_sel:[0,0,1]
	v_mul_f32_e32 v10, s98, v75
	v_mul_f32_e32 v39, s98, v79
	v_mov_b32_e32 v42, v11
	v_cvt_pk_fp8_f32 v42, v10, v39
	v_mul_f32_e32 v10, s98, v91
	v_mul_f32_e32 v39, s98, v95
	v_mov_b32_e32 v43, v11
	v_cvt_pk_fp8_f32 v43, v10, v39
	v_mul_f32_e32 v45, s98, v87
	v_mul_f32_e32 v10, s98, v99
	v_mul_f32_e32 v39, s98, v103
	v_cvt_pk_fp8_f32 v42, v44, v45 op_sel:[0,0,1]
	v_cvt_pk_fp8_f32 v43, v10, v39 op_sel:[0,0,1]
	global_store_dwordx4 v[226:227], v[104:107], off
	global_store_dwordx4 v[226:227], v[108:111], off offset:16
	global_store_dwordx4 v[226:227], v[112:115], off offset:32
	global_store_dwordx4 v[226:227], v[40:43], off offset:48
	s_mov_b32 s99, 2
	s_waitcnt vmcnt(20)
	s_andn2_b32 s12, 1, s64
	s_mulk_i32 s12, 0x4600
	s_add_i32 s12, s12, 0
	v_add_u32_e32 v10, s12, v33
	v_add3_u32 v22, s12, v31, v32
	v_add3_u32 v10, v10, v34, s34
	ds_write_b128 v22, v[0:3]
	ds_write2_b64 v10, v[4:5], v[6:7] offset1:1
	s_branch .LBB0_2376
.Lp13_st1c:
	s_waitcnt vmcnt(17)
	v_mul_f32_e32 v10, s98, v40
	s_waitcnt vmcnt(16)
	v_mul_f32_e32 v39, s98, v44
	v_cvt_pk_fp8_f32 v104, v10, v39
	s_waitcnt vmcnt(15)
	v_mul_f32_e32 v40, s98, v48
	s_waitcnt vmcnt(14)
	v_mul_f32_e32 v44, s98, v52
	s_waitcnt vmcnt(13)
	v_mul_f32_e32 v10, s98, v56
	v_cvt_pk_fp8_f32 v104, v40, v44 op_sel:[0,0,1]
	s_waitcnt vmcnt(12)
	v_mul_f32_e32 v39, s98, v60
	v_cvt_pk_fp8_f32 v105, v10, v39
	s_waitcnt vmcnt(11)
	v_mul_f32_e32 v10, s98, v64
	s_waitcnt vmcnt(10)
	v_mul_f32_e32 v39, s98, v68
	v_cvt_pk_fp8_f32 v105, v10, v39 op_sel:[0,0,1]
	s_waitcnt vmcnt(9)
	v_mul_f32_e32 v10, s98, v72
	s_waitcnt vmcnt(8)
	v_mul_f32_e32 v39, s98, v76
	v_cvt_pk_fp8_f32 v106, v10, v39
	s_waitcnt vmcnt(7)
	v_mul_f32_e32 v40, s98, v80
	s_waitcnt vmcnt(6)
	v_mul_f32_e32 v44, s98, v84
	s_waitcnt vmcnt(5)
	v_mul_f32_e32 v10, s98, v88
	v_cvt_pk_fp8_f32 v106, v40, v44 op_sel:[0,0,1]
	v_mul_f32_e32 v40, s98, v49
	v_mul_f32_e32 v44, s98, v83
	s_waitcnt vmcnt(4)
	v_mul_f32_e32 v39, s98, v92
	v_cvt_pk_fp8_f32 v107, v10, v39
	s_waitcnt vmcnt(3)
	v_mul_f32_e32 v10, s98, v96
	s_waitcnt vmcnt(2)
	v_mul_f32_e32 v39, s98, v100
	v_cvt_pk_fp8_f32 v107, v10, v39 op_sel:[0,0,1]
	v_mul_f32_e32 v10, s98, v41
	v_mul_f32_e32 v39, s98, v45
	v_cvt_pk_fp8_f32 v108, v10, v39
	v_mul_f32_e32 v10, s98, v57
	v_mul_f32_e32 v39, s98, v61
	v_cvt_pk_fp8_f32 v109, v10, v39
	v_mul_f32_e32 v10, s98, v65
	v_mul_f32_e32 v39, s98, v69
	v_mul_f32_e32 v41, s98, v53
	v_cvt_pk_fp8_f32 v109, v10, v39 op_sel:[0,0,1]
	v_mul_f32_e32 v10, s98, v73
	v_mul_f32_e32 v39, s98, v77
	v_cvt_pk_fp8_f32 v110, v10, v39
	v_mul_f32_e32 v10, s98, v89
	v_mul_f32_e32 v39, s98, v93
	v_cvt_pk_fp8_f32 v111, v10, v39
	v_mul_f32_e32 v10, s98, v97
	v_mul_f32_e32 v39, s98, v101
	v_cvt_pk_fp8_f32 v108, v40, v41 op_sel:[0,0,1]
	v_cvt_pk_fp8_f32 v111, v10, v39 op_sel:[0,0,1]
	v_mul_f32_e32 v10, s98, v42
	v_mul_f32_e32 v39, s98, v46
	v_cvt_pk_fp8_f32 v112, v10, v39
	v_mul_f32_e32 v10, s98, v58
	v_mul_f32_e32 v39, s98, v62
	v_cvt_pk_fp8_f32 v113, v10, v39
	v_mul_f32_e32 v10, s98, v66
	v_mul_f32_e32 v39, s98, v70
	v_mul_f32_e32 v40, s98, v81
	v_cvt_pk_fp8_f32 v113, v10, v39 op_sel:[0,0,1]
	v_mul_f32_e32 v10, s98, v74
	v_mul_f32_e32 v39, s98, v78
	v_cvt_pk_fp8_f32 v114, v10, v39
	v_mul_f32_e32 v10, s98, v90
	v_mul_f32_e32 v39, s98, v94
	v_cvt_pk_fp8_f32 v115, v10, v39
	v_mul_f32_e32 v41, s98, v85
	v_cvt_pk_fp8_f32 v110, v40, v41 op_sel:[0,0,1]
	v_mul_f32_e32 v40, s98, v50
	v_mul_f32_e32 v41, s98, v54
	v_cvt_pk_fp8_f32 v112, v40, v41 op_sel:[0,0,1]
	v_mul_f32_e32 v40, s98, v82
	v_mul_f32_e32 v41, s98, v86
	v_mul_f32_e32 v10, s98, v98
	v_mul_f32_e32 v39, s98, v102
	v_cvt_pk_fp8_f32 v114, v40, v41 op_sel:[0,0,1]
	v_cvt_pk_fp8_f32 v115, v10, v39 op_sel:[0,0,1]
	v_mul_f32_e32 v10, s98, v43
	v_mul_f32_e32 v39, s98, v47
	v_mov_b32_e32 v40, v11
	v_cvt_pk_fp8_f32 v40, v10, v39
	v_mul_f32_e32 v10, s98, v59
	v_mul_f32_e32 v39, s98, v63
	v_mov_b32_e32 v41, v11
	v_cvt_pk_fp8_f32 v41, v10, v39
	v_mul_f32_e32 v42, s98, v51
	v_mul_f32_e32 v43, s98, v55
	v_mul_f32_e32 v10, s98, v67
	v_mul_f32_e32 v39, s98, v71
	v_cvt_pk_fp8_f32 v40, v42, v43 op_sel:[0,0,1]
	v_cvt_pk_fp8_f32 v41, v10, v39 op_sel:[0,0,1]
	v_mul_f32_e32 v10, s98, v75
	v_mul_f32_e32 v39, s98, v79
	v_mov_b32_e32 v42, v11
	v_cvt_pk_fp8_f32 v42, v10, v39
	v_mul_f32_e32 v10, s98, v91
	v_mul_f32_e32 v39, s98, v95
	v_mov_b32_e32 v43, v11
	v_cvt_pk_fp8_f32 v43, v10, v39
	v_mul_f32_e32 v45, s98, v87
	v_mul_f32_e32 v10, s98, v99
	v_mul_f32_e32 v39, s98, v103
	v_cvt_pk_fp8_f32 v42, v44, v45 op_sel:[0,0,1]
	v_cvt_pk_fp8_f32 v43, v10, v39 op_sel:[0,0,1]
	global_store_dwordx4 v[226:227], v[104:107], off
	global_store_dwordx4 v[226:227], v[108:111], off offset:16
	global_store_dwordx4 v[226:227], v[112:115], off offset:32
	global_store_dwordx4 v[226:227], v[40:43], off offset:48
	s_mov_b32 s99, 0
	s_waitcnt vmcnt(4)
	s_andn2_b32 s12, 1, s64
	s_mulk_i32 s12, 0x4600
	s_add_i32 s12, s12, 0
	v_add_u32_e32 v10, s12, v33
	v_add3_u32 v22, s12, v31, v32
	v_add3_u32 v10, v10, v34, s34
	ds_write_b128 v22, v[0:3]
	ds_write2_b64 v10, v[4:5], v[6:7] offset1:1
	s_branch .LBB0_2376
.Lp13_st2:
	s_cmp_gt_i32 s3, 0x16fff
	s_cbranch_scc1 .Lp13_st2c
	s_add_i32 s12, s63, 1
	s_cmp_ge_u32 s12, s54
	s_cbranch_scc1 .Lp13_st2c
	s_ashr_i32 s12, s3, 10
	s_mul_hi_i32 s18, s12, 0x55555556
	s_lshr_b32 s19, s18, 31
	s_add_i32 s20, s18, s19
	s_mul_i32 s18, s20, 3
	s_sub_i32 s24, s12, s18
	s_lshl_b32 s12, s3, 8
	s_ashr_i32 s25, s24, 31
	s_and_b32 s12, s12, 0x700
	s_lshl_b64 s[18:19], s[24:25], 3
	s_add_u32 s22, s0, s18
	s_addc_u32 s23, s1, s19
	s_ashr_i32 s21, s20, 31
	v_or_b32_e32 v10, s12, v28
	s_cmp_lg_u32 s24, 2
	s_mov_b64 s[26:27], -1
	s_cbranch_scc0 .Lp13_i3_2381
	v_lshlrev_b32_e32 v226, 1, v10
	s_lshl_b64 s[18:19], s[20:21], 23
	v_and_b32_e32 v226, 0xf00, v226
	v_lshl_or_b32 v227, s24, 7, v35
	s_add_u32 s18, s28, s18
	v_add_u32_e32 v226, v227, v226
	s_addc_u32 s19, s29, s19
	s_mov_b64 s[26:27], 0

.Lp13_i3_2384:
	s_lshl_b64 s[24:25], s[24:25], 2
	s_waitcnt lgkmcnt(0)
	s_add_u32 s12, s22, s24
	s_addc_u32 s23, s23, s25
	s_bfe_u32 s24, s3, 0x70003
	s_lshl_b32 s22, s24, 17
	s_add_u32 s22, s12, s22
	s_addc_u32 s23, s23, 0
	v_lshlrev_b32_e32 v10, 2, v10
	v_lshl_add_u64 v[230:231], s[22:23], 0, v[10:11]
	global_load_dwordx4 v[40:43], v10, s[22:23] nt
	s_nop 0
	v_mov_b32_e32 v104, v11
	v_mov_b32_e32 v105, v11
	v_mov_b32_e32 v106, v11
	v_mov_b32_e32 v107, v11
	v_mov_b32_e32 v108, v11
	v_mov_b32_e32 v109, v11
	v_mov_b32_e32 v110, v11
	v_mov_b32_e32 v111, v11
	v_mov_b32_e32 v112, v11
	v_mov_b32_e32 v113, v11
	v_mov_b32_e32 v114, v11
	v_mov_b32_e32 v115, v11
	s_mul_i32 s12, s20, s24
	v_ashrrev_i32_e32 v227, 31, v226
	v_lshl_add_u64 v[226:227], s[12:13], 0, v[226:227]
	v_lshl_add_u64 v[226:227], v[226:227], 4, s[18:19]
	s_mov_b32 s98, s21
	s_addk_i32 s3, 0x400
	s_waitcnt vmcnt(18)
	v_add_co_u32_e32 v44, vcc, s35, v230
	v_addc_co_u32_e32 v45, vcc, 0, v231, vcc
	global_load_dwordx4 v[44:47], v[44:45], off nt
	s_nop 0
	v_mul_f32_e32 v192, s100, v116
	s_waitcnt vmcnt(18)
	v_add_co_u32_e32 v48, vcc, s36, v230
	v_addc_co_u32_e32 v49, vcc, 0, v231, vcc
	global_load_dwordx4 v[48:51], v[48:49], off nt
	s_nop 0
	v_mul_f32_e32 v196, s100, v120
	v_cvt_pk_fp8_f32 v180, v192, v196
	s_waitcnt vmcnt(18)
	v_add_co_u32_e32 v52, vcc, s37, v230
	v_addc_co_u32_e32 v53, vcc, 0, v231, vcc
	global_load_dwordx4 v[52:55], v[52:53], off nt
	s_nop 0
	v_mul_f32_e32 v116, s100, v124
	s_waitcnt vmcnt(18)
	v_add_co_u32_e32 v56, vcc, s38, v230
	v_addc_co_u32_e32 v57, vcc, 0, v231, vcc
	global_load_dwordx4 v[56:59], v[56:57], off nt
	s_nop 0
	v_mul_f32_e32 v120, s100, v128
	s_waitcnt vmcnt(18)
	v_add_co_u32_e32 v60, vcc, s39, v230
	v_addc_co_u32_e32 v61, vcc, 0, v231, vcc
	global_load_dwordx4 v[60:63], v[60:61], off nt
	s_nop 0
	v_mul_f32_e32 v192, s100, v132
	v_cvt_pk_fp8_f32 v180, v116, v120 op_sel:[0,0,1]
	s_waitcnt vmcnt(18)
	v_add_co_u32_e32 v64, vcc, s40, v230
	v_addc_co_u32_e32 v65, vcc, 0, v231, vcc
	global_load_dwordx4 v[64:67], v[64:65], off nt
	s_nop 0
	v_mul_f32_e32 v196, s100, v136
	v_cvt_pk_fp8_f32 v181, v192, v196
	s_waitcnt vmcnt(18)
	v_add_co_u32_e32 v68, vcc, s41, v230
	v_addc_co_u32_e32 v69, vcc, 0, v231, vcc
	global_load_dwordx4 v[68:71], v[68:69], off nt
	s_nop 0
	v_mul_f32_e32 v192, s100, v140
	s_waitcnt vmcnt(18)
	v_add_co_u32_e32 v72, vcc, s42, v230
	v_addc_co_u32_e32 v73, vcc, 0, v231, vcc
	global_load_dwordx4 v[72:75], v[72:73], off nt
	s_nop 0
	v_mul_f32_e32 v196, s100, v144
	v_cvt_pk_fp8_f32 v181, v192, v196 op_sel:[0,0,1]
	s_waitcnt vmcnt(18)
	v_add_co_u32_e32 v76, vcc, s43, v230
	v_addc_co_u32_e32 v77, vcc, 0, v231, vcc
	global_load_dwordx4 v[76:79], v[76:77], off nt
	s_nop 0
	v_mul_f32_e32 v192, s100, v148
	s_waitcnt vmcnt(18)
	v_add_co_u32_e32 v80, vcc, s44, v230
	v_addc_co_u32_e32 v81, vcc, 0, v231, vcc
	global_load_dwordx4 v[80:83], v[80:81], off nt
	s_nop 0
	v_mul_f32_e32 v196, s100, v152
	v_cvt_pk_fp8_f32 v182, v192, v196
	s_waitcnt vmcnt(18)
	v_add_co_u32_e32 v84, vcc, s45, v230
	v_addc_co_u32_e32 v85, vcc, 0, v231, vcc
	global_load_dwordx4 v[84:87], v[84:85], off nt
	s_nop 0
	v_mul_f32_e32 v116, s100, v156
	s_waitcnt vmcnt(18)
	v_add_co_u32_e32 v88, vcc, s46, v230
	v_addc_co_u32_e32 v89, vcc, 0, v231, vcc
	global_load_dwordx4 v[88:91], v[88:89], off nt
	s_nop 0
	v_mul_f32_e32 v120, s100, v160
	s_waitcnt vmcnt(18)
	v_add_co_u32_e32 v92, vcc, s47, v230
	v_addc_co_u32_e32 v93, vcc, 0, v231, vcc
	global_load_dwordx4 v[92:95], v[92:93], off nt
	s_nop 0
	v_mul_f32_e32 v192, s100, v164
	v_cvt_pk_fp8_f32 v182, v116, v120 op_sel:[0,0,1]
	v_mul_f32_e32 v116, s100, v125
	v_mul_f32_e32 v120, s100, v159
	s_waitcnt vmcnt(18)
	v_add_co_u32_e32 v96, vcc, s48, v230
	v_addc_co_u32_e32 v97, vcc, 0, v231, vcc
	global_load_dwordx4 v[96:99], v[96:97], off nt
	s_nop 0
	v_mul_f32_e32 v196, s100, v168
	v_cvt_pk_fp8_f32 v183, v192, v196
	s_waitcnt vmcnt(18)
	v_add_co_u32_e32 v100, vcc, s49, v230
	v_addc_co_u32_e32 v101, vcc, 0, v231, vcc
	global_load_dwordx4 v[100:103], v[100:101], off nt
	s_nop 0
	v_mul_f32_e32 v192, s100, v172
	s_waitcnt vmcnt(18)
	v_mul_f32_e32 v196, s100, v176
	v_cvt_pk_fp8_f32 v183, v192, v196 op_sel:[0,0,1]
	v_mul_f32_e32 v192, s100, v117
	v_mul_f32_e32 v196, s100, v121
	v_cvt_pk_fp8_f32 v184, v192, v196
	v_mul_f32_e32 v192, s100, v133
	v_mul_f32_e32 v196, s100, v137
	v_cvt_pk_fp8_f32 v185, v192, v196
	v_mul_f32_e32 v192, s100, v141
	v_mul_f32_e32 v196, s100, v145
	v_mul_f32_e32 v117, s100, v129
	v_cvt_pk_fp8_f32 v185, v192, v196 op_sel:[0,0,1]
	v_mul_f32_e32 v192, s100, v149
	v_mul_f32_e32 v196, s100, v153
	v_cvt_pk_fp8_f32 v186, v192, v196
	v_mul_f32_e32 v192, s100, v165
	v_mul_f32_e32 v196, s100, v169
	v_cvt_pk_fp8_f32 v187, v192, v196
	v_mul_f32_e32 v192, s100, v173
	v_mul_f32_e32 v196, s100, v177
	v_cvt_pk_fp8_f32 v184, v116, v117 op_sel:[0,0,1]
	v_cvt_pk_fp8_f32 v187, v192, v196 op_sel:[0,0,1]
	v_mul_f32_e32 v192, s100, v118
	v_mul_f32_e32 v196, s100, v122
	v_cvt_pk_fp8_f32 v188, v192, v196
	v_mul_f32_e32 v192, s100, v134
	v_mul_f32_e32 v196, s100, v138
	v_cvt_pk_fp8_f32 v189, v192, v196
	v_mul_f32_e32 v192, s100, v142
	v_mul_f32_e32 v196, s100, v146
	v_mul_f32_e32 v116, s100, v157
	v_cvt_pk_fp8_f32 v189, v192, v196 op_sel:[0,0,1]
	v_mul_f32_e32 v192, s100, v150
	v_mul_f32_e32 v196, s100, v154
	v_cvt_pk_fp8_f32 v190, v192, v196
	v_mul_f32_e32 v192, s100, v166
	v_mul_f32_e32 v196, s100, v170
	v_cvt_pk_fp8_f32 v191, v192, v196
	v_mul_f32_e32 v117, s100, v161
	v_cvt_pk_fp8_f32 v186, v116, v117 op_sel:[0,0,1]
	v_mul_f32_e32 v116, s100, v126
	v_mul_f32_e32 v117, s100, v130
	v_cvt_pk_fp8_f32 v188, v116, v117 op_sel:[0,0,1]
	v_mul_f32_e32 v116, s100, v158
	v_mul_f32_e32 v117, s100, v162
	v_mul_f32_e32 v192, s100, v174
	v_mul_f32_e32 v196, s100, v178
	v_cvt_pk_fp8_f32 v190, v116, v117 op_sel:[0,0,1]
	v_cvt_pk_fp8_f32 v191, v192, v196 op_sel:[0,0,1]
	v_mul_f32_e32 v192, s100, v119
	v_mul_f32_e32 v196, s100, v123
	v_mov_b32_e32 v116, v11
	v_cvt_pk_fp8_f32 v116, v192, v196
	v_mul_f32_e32 v192, s100, v135
	v_mul_f32_e32 v196, s100, v139
	v_mov_b32_e32 v117, v11
	v_cvt_pk_fp8_f32 v117, v192, v196
	v_mul_f32_e32 v118, s100, v127
	v_mul_f32_e32 v119, s100, v131
	v_mul_f32_e32 v192, s100, v143
	v_mul_f32_e32 v196, s100, v147
	v_cvt_pk_fp8_f32 v116, v118, v119 op_sel:[0,0,1]
	v_cvt_pk_fp8_f32 v117, v192, v196 op_sel:[0,0,1]
	v_mul_f32_e32 v192, s100, v151
	v_mul_f32_e32 v196, s100, v155
	v_mov_b32_e32 v118, v11
	v_cvt_pk_fp8_f32 v118, v192, v196
	v_mul_f32_e32 v192, s100, v167
	v_mul_f32_e32 v196, s100, v171
	v_mov_b32_e32 v119, v11
	v_cvt_pk_fp8_f32 v119, v192, v196
	v_mul_f32_e32 v121, s100, v163
	v_mul_f32_e32 v192, s100, v175
	v_mul_f32_e32 v196, s100, v179
	v_cvt_pk_fp8_f32 v118, v120, v121 op_sel:[0,0,1]
	v_cvt_pk_fp8_f32 v119, v192, v196 op_sel:[0,0,1]
	global_store_dwordx4 v[228:229], v[180:183], off
	global_store_dwordx4 v[228:229], v[184:187], off offset:16
	global_store_dwordx4 v[228:229], v[188:191], off offset:32
	global_store_dwordx4 v[228:229], v[116:119], off offset:48
	s_mov_b32 s99, 1
	s_waitcnt vmcnt(20)
	s_andn2_b32 s12, 1, s64
	s_mulk_i32 s12, 0x4600
	s_add_i32 s12, s12, 0
	v_add_u32_e32 v10, s12, v33
	v_add3_u32 v22, s12, v31, v32
	v_add3_u32 v10, v10, v34, s34
	ds_write_b128 v22, v[0:3]
	ds_write2_b64 v10, v[4:5], v[6:7] offset1:1
	s_branch .LBB0_2376
.Lp13_st2c:
	s_waitcnt vmcnt(17)
	v_mul_f32_e32 v192, s100, v116
	s_waitcnt vmcnt(16)
	v_mul_f32_e32 v196, s100, v120
	v_cvt_pk_fp8_f32 v180, v192, v196
	s_waitcnt vmcnt(15)
	v_mul_f32_e32 v116, s100, v124
	s_waitcnt vmcnt(14)
	v_mul_f32_e32 v120, s100, v128
	s_waitcnt vmcnt(13)
	v_mul_f32_e32 v192, s100, v132
	v_cvt_pk_fp8_f32 v180, v116, v120 op_sel:[0,0,1]
	s_waitcnt vmcnt(12)
	v_mul_f32_e32 v196, s100, v136
	v_cvt_pk_fp8_f32 v181, v192, v196
	s_waitcnt vmcnt(11)
	v_mul_f32_e32 v192, s100, v140
	s_waitcnt vmcnt(10)
	v_mul_f32_e32 v196, s100, v144
	v_cvt_pk_fp8_f32 v181, v192, v196 op_sel:[0,0,1]
	s_waitcnt vmcnt(9)
	v_mul_f32_e32 v192, s100, v148
	s_waitcnt vmcnt(8)
	v_mul_f32_e32 v196, s100, v152
	v_cvt_pk_fp8_f32 v182, v192, v196
	s_waitcnt vmcnt(7)
	v_mul_f32_e32 v116, s100, v156
	s_waitcnt vmcnt(6)
	v_mul_f32_e32 v120, s100, v160
	s_waitcnt vmcnt(5)
	v_mul_f32_e32 v192, s100, v164
	v_cvt_pk_fp8_f32 v182, v116, v120 op_sel:[0,0,1]
	v_mul_f32_e32 v116, s100, v125
	v_mul_f32_e32 v120, s100, v159
	s_waitcnt vmcnt(4)
	v_mul_f32_e32 v196, s100, v168
	v_cvt_pk_fp8_f32 v183, v192, v196
	s_waitcnt vmcnt(3)
	v_mul_f32_e32 v192, s100, v172
	s_waitcnt vmcnt(2)
	v_mul_f32_e32 v196, s100, v176
	v_cvt_pk_fp8_f32 v183, v192, v196 op_sel:[0,0,1]
	v_mul_f32_e32 v192, s100, v117
	v_mul_f32_e32 v196, s100, v121
	v_cvt_pk_fp8_f32 v184, v192, v196
	v_mul_f32_e32 v192, s100, v133
	v_mul_f32_e32 v196, s100, v137
	v_cvt_pk_fp8_f32 v185, v192, v196
	v_mul_f32_e32 v192, s100, v141
	v_mul_f32_e32 v196, s100, v145
	v_mul_f32_e32 v117, s100, v129
	v_cvt_pk_fp8_f32 v185, v192, v196 op_sel:[0,0,1]
	v_mul_f32_e32 v192, s100, v149
	v_mul_f32_e32 v196, s100, v153
	v_cvt_pk_fp8_f32 v186, v192, v196
	v_mul_f32_e32 v192, s100, v165
	v_mul_f32_e32 v196, s100, v169
	v_cvt_pk_fp8_f32 v187, v192, v196
	v_mul_f32_e32 v192, s100, v173
	v_mul_f32_e32 v196, s100, v177
	v_cvt_pk_fp8_f32 v184, v116, v117 op_sel:[0,0,1]
	v_cvt_pk_fp8_f32 v187, v192, v196 op_sel:[0,0,1]
	v_mul_f32_e32 v192, s100, v118
	v_mul_f32_e32 v196, s100, v122
	v_cvt_pk_fp8_f32 v188, v192, v196
	v_mul_f32_e32 v192, s100, v134
	v_mul_f32_e32 v196, s100, v138
	v_cvt_pk_fp8_f32 v189, v192, v196
	v_mul_f32_e32 v192, s100, v142
	v_mul_f32_e32 v196, s100, v146
	v_mul_f32_e32 v116, s100, v157
	v_cvt_pk_fp8_f32 v189, v192, v196 op_sel:[0,0,1]
	v_mul_f32_e32 v192, s100, v150
	v_mul_f32_e32 v196, s100, v154
	v_cvt_pk_fp8_f32 v190, v192, v196
	v_mul_f32_e32 v192, s100, v166
	v_mul_f32_e32 v196, s100, v170
	v_cvt_pk_fp8_f32 v191, v192, v196
	v_mul_f32_e32 v117, s100, v161
	v_cvt_pk_fp8_f32 v186, v116, v117 op_sel:[0,0,1]
	v_mul_f32_e32 v116, s100, v126
	v_mul_f32_e32 v117, s100, v130
	v_cvt_pk_fp8_f32 v188, v116, v117 op_sel:[0,0,1]
	v_mul_f32_e32 v116, s100, v158
	v_mul_f32_e32 v117, s100, v162
	v_mul_f32_e32 v192, s100, v174
	v_mul_f32_e32 v196, s100, v178
	v_cvt_pk_fp8_f32 v190, v116, v117 op_sel:[0,0,1]
	v_cvt_pk_fp8_f32 v191, v192, v196 op_sel:[0,0,1]
	v_mul_f32_e32 v192, s100, v119
	v_mul_f32_e32 v196, s100, v123
	v_mov_b32_e32 v116, v11
	v_cvt_pk_fp8_f32 v116, v192, v196
	v_mul_f32_e32 v192, s100, v135
	v_mul_f32_e32 v196, s100, v139
	v_mov_b32_e32 v117, v11
	v_cvt_pk_fp8_f32 v117, v192, v196
	v_mul_f32_e32 v118, s100, v127
	v_mul_f32_e32 v119, s100, v131
	v_mul_f32_e32 v192, s100, v143
	v_mul_f32_e32 v196, s100, v147
	v_cvt_pk_fp8_f32 v116, v118, v119 op_sel:[0,0,1]
	v_cvt_pk_fp8_f32 v117, v192, v196 op_sel:[0,0,1]
	v_mul_f32_e32 v192, s100, v151
	v_mul_f32_e32 v196, s100, v155
	v_mov_b32_e32 v118, v11
	v_cvt_pk_fp8_f32 v118, v192, v196
	v_mul_f32_e32 v192, s100, v167
	v_mul_f32_e32 v196, s100, v171
	v_mov_b32_e32 v119, v11
	v_cvt_pk_fp8_f32 v119, v192, v196
	v_mul_f32_e32 v121, s100, v163
	v_mul_f32_e32 v192, s100, v175
	v_mul_f32_e32 v196, s100, v179
	v_cvt_pk_fp8_f32 v118, v120, v121 op_sel:[0,0,1]
	v_cvt_pk_fp8_f32 v119, v192, v196 op_sel:[0,0,1]
	global_store_dwordx4 v[228:229], v[180:183], off
	global_store_dwordx4 v[228:229], v[184:187], off offset:16
	global_store_dwordx4 v[228:229], v[188:191], off offset:32
	global_store_dwordx4 v[228:229], v[116:119], off offset:48
	s_mov_b32 s99, 0
	s_waitcnt vmcnt(4)
	s_andn2_b32 s12, 1, s64
	s_mulk_i32 s12, 0x4600
	s_add_i32 s12, s12, 0
	v_add_u32_e32 v10, s12, v33
	v_add3_u32 v22, s12, v31, v32
	v_add3_u32 v10, v10, v34, s34
	ds_write_b128 v22, v[0:3]
	ds_write2_b64 v10, v[4:5], v[6:7] offset1:1
	s_branch .LBB0_2376

.LBB0_2376:
	s_add_i32 s55, s55, 64
	s_cmp_eq_u32 s54, s63
	s_waitcnt lgkmcnt(0)
	s_barrier
	s_cbranch_scc1 .LBB0_2385
	s_mov_b32 s64, s63
	s_branch .LBB0_2372
.LBB0_2378:
	s_branch .LBB0_2376
.LBB0_2385:
	s_add_i32 s12, s50, 0x100
	s_cmpk_gt_i32 s50, 0x4ff
	s_cbranch_scc0 .LBB0_2365

	.amdhsa_kernel _Z4mega6Params
		.amdhsa_group_segment_fixed_size 0
		.amdhsa_private_segment_fixed_size 0
		.amdhsa_kernarg_size 520
		.amdhsa_user_sgpr_count 2
		.amdhsa_user_sgpr_dispatch_ptr 0
		.amdhsa_user_sgpr_queue_ptr 0
		.amdhsa_user_sgpr_kernarg_segment_ptr 1
		.amdhsa_user_sgpr_dispatch_id 0
		.amdhsa_user_sgpr_kernarg_preload_length 0
		.amdhsa_user_sgpr_kernarg_preload_offset 0
		.amdhsa_user_sgpr_private_segment_size 0
		.amdhsa_uses_dynamic_stack 0
		.amdhsa_enable_private_segment 0
		.amdhsa_system_sgpr_workgroup_id_x 1
		.amdhsa_system_sgpr_workgroup_id_y 0
		.amdhsa_system_sgpr_workgroup_id_z 0
		.amdhsa_system_sgpr_workgroup_info 0
		.amdhsa_system_vgpr_workitem_id 0
		.amdhsa_next_free_vgpr 256
		.amdhsa_next_free_sgpr 102
		.amdhsa_accum_offset 256
		.amdhsa_reserve_vcc 1
		.amdhsa_float_round_mode_32 0
		.amdhsa_float_round_mode_16_64 0
		.amdhsa_float_denorm_mode_32 3
		.amdhsa_float_denorm_mode_16_64 3
		.amdhsa_dx10_clamp 1
		.amdhsa_ieee_mode 1
		.amdhsa_fp16_overflow 0
		.amdhsa_tg_split 0
		.amdhsa_exception_fp_ieee_invalid_op 0
		.amdhsa_exception_fp_denorm_src 0
		.amdhsa_exception_fp_ieee_div_zero 0
		.amdhsa_exception_fp_ieee_overflow 0
		.amdhsa_exception_fp_ieee_underflow 0
		.amdhsa_exception_fp_ieee_inexact 0
		.amdhsa_exception_int_div_zero 0
	.end_amdhsa_kernel

amdhsa.kernels:
  - .agpr_count:     0
    .args:
      - .offset:         0
        .size:           264
        .value_kind:     by_value
      - .offset:         264
        .size:           4
        .value_kind:     hidden_block_count_x
      - .offset:         268
        .size:           4
        .value_kind:     hidden_block_count_y
      - .offset:         272
        .size:           4
        .value_kind:     hidden_block_count_z
      - .offset:         276
        .size:           2
        .value_kind:     hidden_group_size_x
      - .offset:         278
        .size:           2
        .value_kind:     hidden_group_size_y
      - .offset:         280
        .size:           2
        .value_kind:     hidden_group_size_z
      - .offset:         282
        .size:           2
        .value_kind:     hidden_remainder_x
      - .offset:         284
        .size:           2
        .value_kind:     hidden_remainder_y
      - .offset:         286
        .size:           2
        .value_kind:     hidden_remainder_z
      - .offset:         304
        .size:           8
        .value_kind:     hidden_global_offset_x
      - .offset:         312
        .size:           8
        .value_kind:     hidden_global_offset_y
      - .offset:         320
        .size:           8
        .value_kind:     hidden_global_offset_z
      - .offset:         328
        .size:           2
        .value_kind:     hidden_grid_dims
      - .offset:         384
        .size:           4
        .value_kind:     hidden_dynamic_lds_size
    .group_segment_fixed_size: 0
    .kernarg_segment_align: 8
    .kernarg_segment_size: 520
    .language:       OpenCL C
    .language_version:
      - 2
      - 0
    .max_flat_workgroup_size: 512
    .name:           _Z4mega6Params
    .private_segment_fixed_size: 0
    .sgpr_count:     108
    .sgpr_spill_count: 4
    .symbol:         _Z4mega6Params.kd
    .uniform_work_group_size: 1
    .uses_dynamic_stack: false
    .vgpr_count:     256
    .vgpr_spill_count: 0
    .wavefront_size: 64
